# scan forward substitution: the ring's first 12 Nab fragments requested in front of the stage-4 barrier (wave 0 idles there)
# baseline (speedup 1.0000x reference)
.LBB0_582:
	s_cmp_eq_u32 s85, 0
	s_cselect_b64 s[34:35], -1, 0
	s_or_b64 s[34:35], s[74:75], s[34:35]
	s_and_b64 vcc, exec, s[34:35]
	s_and_b64 s[98:99], exec, s[30:31]
	s_cbranch_scc1 .Lnabpf_skip_2
	ds_read_b128 v[208:211], v2 offset:58368
	ds_read_b128 v[212:215], v2 offset:58384
	ds_read_b128 v[216:219], v2 offset:58400
	ds_read_b128 v[220:223], v2 offset:58416
	ds_read_b128 v[224:227], v2 offset:58432
	ds_read_b128 v[228:231], v2 offset:58448
	ds_read_b128 v[240:243], v2 offset:58464
	ds_read_b128 v[244:247], v2 offset:58480
	ds_read_b128 v[38:41], v2 offset:58496
	ds_read_b128 v[42:45], v2 offset:58512
	ds_read_b128 v[46:49], v2 offset:58528
	ds_read_b128 v[50:53], v2 offset:58544
.Lnabpf_skip_2:
	s_waitcnt lgkmcnt(0)
	s_barrier
	s_cbranch_vccnz .LBB0_585
	v_cndmask_b32_e64 v3, 0, 1, s[94:95]
	v_lshlrev_b32_e32 v3, 7, v3
	v_readlane_b32 s5, v250, 33
	s_mov_b32 s8, 0x9000
	v_mov_b32_e32 v38, v121
	v_add_u32_e32 v3, s5, v3
	s_add_i32 s5, s85, -1
	s_bitcmp0_b32 s5, 0
	s_movk_i32 s5, 0x6c00
	s_cselect_b32 s5, s5, 0x13600
	s_cselect_b32 s34, s8, 0x14800
	v_add_u32_e32 v4, s34, v120
	v_add_u32_e32 v5, s5, v120
	v_readlane_b32 s5, v250, 32
	ds_read_b32 v208, v38
	ds_read_b32 v209, v3
	ds_read_u16 v210, v5
	ds_read_u16 v211, v4

.LBB0_585:
	s_and_b64 vcc, exec, s[30:31]
	s_cbranch_vccnz .LBB0_587
	ds_read2st64_b32 v[176:177], v106 offset0:244 offset1:245
	ds_read2st64_b32 v[178:179], v106 offset0:246 offset1:247
	ds_read2st64_b32 v[180:181], v106 offset0:248 offset1:249
	ds_read2st64_b32 v[182:183], v106 offset0:250 offset1:251
	ds_read2st64_b32 v[184:185], v106 offset0:252 offset1:253
	ds_read2st64_b32 v[186:187], v106 offset0:254 offset1:255
	ds_read2st64_b32 v[188:189], v107 offset0:12 offset1:13
	ds_read2st64_b32 v[190:191], v107 offset0:14 offset1:15
	ds_read2st64_b32 v[192:193], v107 offset0:16 offset1:17
	ds_read2st64_b32 v[194:195], v107 offset0:18 offset1:19
	ds_read2st64_b32 v[196:197], v107 offset0:20 offset1:21
	ds_read2st64_b32 v[198:199], v107 offset0:22 offset1:23
	ds_read2st64_b32 v[200:201], v107 offset0:24 offset1:25
	ds_read2st64_b32 v[202:203], v107 offset0:26 offset1:27
	ds_read2st64_b32 v[204:205], v107 offset0:28 offset1:29
	s_waitcnt lgkmcnt(14)
	ds_read2st64_b32 v[206:207], v107 offset0:30 offset1:31
	v_pk_fma_f32 v[176:177], v[208:209], v[176:177], v[176:177] op_sel:[0,0,0] op_sel_hi:[1,0,1]
	s_waitcnt lgkmcnt(14)
	v_pk_fma_f32 v[178:179], v[210:211], v[176:177], v[178:179] op_sel:[0,0,0] op_sel_hi:[1,0,1]
	v_cvt_pk_bf16_f32 v3, v176, v2
	ds_write_b16 v108, v3 offset:32256
	s_waitcnt lgkmcnt(14)
	ds_read_b128 v[208:211], v2 offset:58560
	v_pk_fma_f32 v[180:181], v[212:213], v[176:177], v[180:181] op_sel:[0,0,0] op_sel_hi:[1,0,1]
	s_waitcnt lgkmcnt(14)
	v_pk_fma_f32 v[182:183], v[214:215], v[176:177], v[182:183] op_sel:[0,0,0] op_sel_hi:[1,0,1]
	ds_read_b128 v[212:215], v2 offset:58576
	s_waitcnt lgkmcnt(14)
	v_pk_fma_f32 v[184:185], v[216:217], v[176:177], v[184:185] op_sel:[0,0,0] op_sel_hi:[1,0,1]
	s_waitcnt lgkmcnt(13)
	v_pk_fma_f32 v[186:187], v[218:219], v[176:177], v[186:187] op_sel:[0,0,0] op_sel_hi:[1,0,1]
	ds_read_b128 v[216:219], v2 offset:58592
	s_waitcnt lgkmcnt(13)
	v_pk_fma_f32 v[188:189], v[220:221], v[176:177], v[188:189] op_sel:[0,0,0] op_sel_hi:[1,0,1]
	s_waitcnt lgkmcnt(12)
	v_pk_fma_f32 v[190:191], v[222:223], v[176:177], v[190:191] op_sel:[0,0,0] op_sel_hi:[1,0,1]
	ds_read_b128 v[220:223], v2 offset:58608
	s_waitcnt lgkmcnt(12)
	v_pk_fma_f32 v[192:193], v[224:225], v[176:177], v[192:193] op_sel:[0,0,0] op_sel_hi:[1,0,1]
	s_waitcnt lgkmcnt(11)
	v_pk_fma_f32 v[194:195], v[226:227], v[176:177], v[194:195] op_sel:[0,0,0] op_sel_hi:[1,0,1]
	ds_read_b128 v[224:227], v2 offset:58624
	s_waitcnt lgkmcnt(11)
	v_pk_fma_f32 v[196:197], v[228:229], v[176:177], v[196:197] op_sel:[0,0,0] op_sel_hi:[1,0,1]
	s_waitcnt lgkmcnt(10)
	v_pk_fma_f32 v[198:199], v[230:231], v[176:177], v[198:199] op_sel:[0,0,0] op_sel_hi:[1,0,1]
	ds_read_b128 v[228:231], v2 offset:58640
	s_waitcnt lgkmcnt(10)
	v_pk_fma_f32 v[200:201], v[240:241], v[176:177], v[200:201] op_sel:[0,0,0] op_sel_hi:[1,0,1]
	s_waitcnt lgkmcnt(9)
	v_pk_fma_f32 v[202:203], v[242:243], v[176:177], v[202:203] op_sel:[0,0,0] op_sel_hi:[1,0,1]
	ds_read_b128 v[240:243], v2 offset:58656
	s_waitcnt lgkmcnt(9)
	v_pk_fma_f32 v[204:205], v[244:245], v[176:177], v[204:205] op_sel:[0,0,0] op_sel_hi:[1,0,1]
	s_waitcnt lgkmcnt(8)
	v_pk_fma_f32 v[206:207], v[246:247], v[176:177], v[206:207] op_sel:[0,0,0] op_sel_hi:[1,0,1]
	ds_read_b128 v[244:247], v2 offset:58672
	v_pk_fma_f32 v[178:179], v[40:41], v[176:177], v[178:179] op_sel:[0,1,0] op_sel_hi:[1,1,1]
	v_cvt_pk_bf16_f32 v232, v177, v2
	ds_write_b16 v108, v232 offset:32400
	ds_read_b128 v[38:41], v2 offset:58688
	v_pk_fma_f32 v[180:181], v[42:43], v[176:177], v[180:181] op_sel:[0,1,0] op_sel_hi:[1,1,1]
	v_pk_fma_f32 v[182:183], v[44:45], v[176:177], v[182:183] op_sel:[0,1,0] op_sel_hi:[1,1,1]
	ds_read_b128 v[42:45], v2 offset:58704
	v_pk_fma_f32 v[184:185], v[46:47], v[176:177], v[184:185] op_sel:[0,1,0] op_sel_hi:[1,1,1]
	v_pk_fma_f32 v[186:187], v[48:49], v[176:177], v[186:187] op_sel:[0,1,0] op_sel_hi:[1,1,1]
	ds_read_b128 v[46:49], v2 offset:58720
	v_pk_fma_f32 v[188:189], v[50:51], v[176:177], v[188:189] op_sel:[0,1,0] op_sel_hi:[1,1,1]
	v_pk_fma_f32 v[190:191], v[52:53], v[176:177], v[190:191] op_sel:[0,1,0] op_sel_hi:[1,1,1]
	ds_read_b128 v[50:53], v2 offset:58736
	s_waitcnt lgkmcnt(12)
	v_pk_fma_f32 v[192:193], v[208:209], v[176:177], v[192:193] op_sel:[0,1,0] op_sel_hi:[1,1,1]
	v_pk_fma_f32 v[194:195], v[210:211], v[176:177], v[194:195] op_sel:[0,1,0] op_sel_hi:[1,1,1]
	ds_read_b128 v[208:211], v2 offset:58768
	s_waitcnt lgkmcnt(12)
	v_pk_fma_f32 v[196:197], v[212:213], v[176:177], v[196:197] op_sel:[0,1,0] op_sel_hi:[1,1,1]
	v_pk_fma_f32 v[198:199], v[214:215], v[176:177], v[198:199] op_sel:[0,1,0] op_sel_hi:[1,1,1]
	ds_read_b128 v[212:215], v2 offset:58784
	s_waitcnt lgkmcnt(12)
	v_pk_fma_f32 v[200:201], v[216:217], v[176:177], v[200:201] op_sel:[0,1,0] op_sel_hi:[1,1,1]
	v_pk_fma_f32 v[202:203], v[218:219], v[176:177], v[202:203] op_sel:[0,1,0] op_sel_hi:[1,1,1]
	ds_read_b128 v[216:219], v2 offset:58800
	s_waitcnt lgkmcnt(12)
	v_pk_fma_f32 v[204:205], v[220:221], v[176:177], v[204:205] op_sel:[0,1,0] op_sel_hi:[1,1,1]
	v_pk_fma_f32 v[206:207], v[222:223], v[176:177], v[206:207] op_sel:[0,1,0] op_sel_hi:[1,1,1]
	ds_read_b128 v[220:223], v2 offset:58816
	s_waitcnt lgkmcnt(12)
	v_pk_fma_f32 v[178:179], v[226:227], v[178:179], v[178:179] op_sel:[0,0,0] op_sel_hi:[1,0,1]
	v_cvt_pk_bf16_f32 v233, v178, v2
	ds_write_b16 v108, v233 offset:32544
	ds_read_b128 v[224:227], v2 offset:58832
	s_waitcnt lgkmcnt(13)
	v_pk_fma_f32 v[180:181], v[228:229], v[178:179], v[180:181] op_sel:[0,0,0] op_sel_hi:[1,0,1]
	v_pk_fma_f32 v[182:183], v[230:231], v[178:179], v[182:183] op_sel:[0,0,0] op_sel_hi:[1,0,1]
	ds_read_b128 v[228:231], v2 offset:58848
	s_waitcnt lgkmcnt(13)
	v_pk_fma_f32 v[184:185], v[240:241], v[178:179], v[184:185] op_sel:[0,0,0] op_sel_hi:[1,0,1]
	v_pk_fma_f32 v[186:187], v[242:243], v[178:179], v[186:187] op_sel:[0,0,0] op_sel_hi:[1,0,1]
	ds_read_b128 v[240:243], v2 offset:58864
	s_waitcnt lgkmcnt(13)
	v_pk_fma_f32 v[188:189], v[244:245], v[178:179], v[188:189] op_sel:[0,0,0] op_sel_hi:[1,0,1]
	v_pk_fma_f32 v[190:191], v[246:247], v[178:179], v[190:191] op_sel:[0,0,0] op_sel_hi:[1,0,1]
	ds_read_b128 v[244:247], v2 offset:58896
	s_waitcnt lgkmcnt(12)
	v_pk_fma_f32 v[192:193], v[38:39], v[178:179], v[192:193] op_sel:[0,0,0] op_sel_hi:[1,0,1]
	v_pk_fma_f32 v[194:195], v[40:41], v[178:179], v[194:195] op_sel:[0,0,0] op_sel_hi:[1,0,1]
	ds_read_b128 v[38:41], v2 offset:58912
	s_waitcnt lgkmcnt(12)
	v_pk_fma_f32 v[196:197], v[42:43], v[178:179], v[196:197] op_sel:[0,0,0] op_sel_hi:[1,0,1]
	v_pk_fma_f32 v[198:199], v[44:45], v[178:179], v[198:199] op_sel:[0,0,0] op_sel_hi:[1,0,1]
	ds_read_b128 v[42:45], v2 offset:58928
	s_waitcnt lgkmcnt(12)
	v_pk_fma_f32 v[200:201], v[46:47], v[178:179], v[200:201] op_sel:[0,0,0] op_sel_hi:[1,0,1]
	v_pk_fma_f32 v[202:203], v[48:49], v[178:179], v[202:203] op_sel:[0,0,0] op_sel_hi:[1,0,1]
	ds_read_b128 v[46:49], v2 offset:58944
	s_waitcnt lgkmcnt(12)
	v_pk_fma_f32 v[204:205], v[50:51], v[178:179], v[204:205] op_sel:[0,0,0] op_sel_hi:[1,0,1]
	v_pk_fma_f32 v[206:207], v[52:53], v[178:179], v[206:207] op_sel:[0,0,0] op_sel_hi:[1,0,1]
	ds_read_b128 v[50:53], v2 offset:58960
	s_waitcnt lgkmcnt(12)
	v_pk_fma_f32 v[180:181], v[208:209], v[178:179], v[180:181] op_sel:[0,1,0] op_sel_hi:[1,1,1]
	v_pk_fma_f32 v[182:183], v[210:211], v[178:179], v[182:183] op_sel:[0,1,0] op_sel_hi:[1,1,1]
	v_cvt_pk_bf16_f32 v248, v179, v2
	ds_write_b16 v108, v248 offset:32688
	ds_read_b128 v[208:211], v2 offset:58976
	s_waitcnt lgkmcnt(13)
	v_pk_fma_f32 v[184:185], v[212:213], v[178:179], v[184:185] op_sel:[0,1,0] op_sel_hi:[1,1,1]
	v_pk_fma_f32 v[186:187], v[214:215], v[178:179], v[186:187] op_sel:[0,1,0] op_sel_hi:[1,1,1]
	ds_read_b128 v[212:215], v2 offset:58992
	s_waitcnt lgkmcnt(13)
	v_pk_fma_f32 v[188:189], v[216:217], v[178:179], v[188:189] op_sel:[0,1,0] op_sel_hi:[1,1,1]
	v_pk_fma_f32 v[190:191], v[218:219], v[178:179], v[190:191] op_sel:[0,1,0] op_sel_hi:[1,1,1]
	ds_read_b128 v[216:219], v2 offset:59024
	s_waitcnt lgkmcnt(13)
	v_pk_fma_f32 v[192:193], v[220:221], v[178:179], v[192:193] op_sel:[0,1,0] op_sel_hi:[1,1,1]
	v_pk_fma_f32 v[194:195], v[222:223], v[178:179], v[194:195] op_sel:[0,1,0] op_sel_hi:[1,1,1]
	ds_read_b128 v[220:223], v2 offset:59040
	s_waitcnt lgkmcnt(12)
	v_pk_fma_f32 v[196:197], v[224:225], v[178:179], v[196:197] op_sel:[0,1,0] op_sel_hi:[1,1,1]
	v_pk_fma_f32 v[198:199], v[226:227], v[178:179], v[198:199] op_sel:[0,1,0] op_sel_hi:[1,1,1]
	ds_read_b128 v[224:227], v2 offset:59056
	s_waitcnt lgkmcnt(12)
	v_pk_fma_f32 v[200:201], v[228:229], v[178:179], v[200:201] op_sel:[0,1,0] op_sel_hi:[1,1,1]
	v_pk_fma_f32 v[202:203], v[230:231], v[178:179], v[202:203] op_sel:[0,1,0] op_sel_hi:[1,1,1]
	ds_read_b128 v[228:231], v2 offset:59072
	s_waitcnt lgkmcnt(12)
	v_pk_fma_f32 v[204:205], v[240:241], v[178:179], v[204:205] op_sel:[0,1,0] op_sel_hi:[1,1,1]
	v_pk_fma_f32 v[206:207], v[242:243], v[178:179], v[206:207] op_sel:[0,1,0] op_sel_hi:[1,1,1]
	ds_read_b128 v[240:243], v2 offset:59088
	s_waitcnt lgkmcnt(12)
	v_pk_fma_f32 v[180:181], v[244:245], v[180:181], v[180:181] op_sel:[0,0,0] op_sel_hi:[1,0,1]
	v_pk_fma_f32 v[182:183], v[246:247], v[180:181], v[182:183] op_sel:[0,0,0] op_sel_hi:[1,0,1]
	v_cvt_pk_bf16_f32 v3, v180, v2
	ds_write_b16 v108, v3 offset:32832
	ds_read_b128 v[244:247], v2 offset:59104
	s_waitcnt lgkmcnt(13)
	v_pk_fma_f32 v[184:185], v[38:39], v[180:181], v[184:185] op_sel:[0,0,0] op_sel_hi:[1,0,1]
	v_pk_fma_f32 v[186:187], v[40:41], v[180:181], v[186:187] op_sel:[0,0,0] op_sel_hi:[1,0,1]
	ds_read_b128 v[38:41], v2 offset:59120
	s_waitcnt lgkmcnt(13)
	v_pk_fma_f32 v[188:189], v[42:43], v[180:181], v[188:189] op_sel:[0,0,0] op_sel_hi:[1,0,1]
	v_pk_fma_f32 v[190:191], v[44:45], v[180:181], v[190:191] op_sel:[0,0,0] op_sel_hi:[1,0,1]
	ds_read_b128 v[42:45], v2 offset:59152
	s_waitcnt lgkmcnt(13)
	v_pk_fma_f32 v[192:193], v[46:47], v[180:181], v[192:193] op_sel:[0,0,0] op_sel_hi:[1,0,1]
	v_pk_fma_f32 v[194:195], v[48:49], v[180:181], v[194:195] op_sel:[0,0,0] op_sel_hi:[1,0,1]
	ds_read_b128 v[46:49], v2 offset:59168
	s_waitcnt lgkmcnt(13)
	v_pk_fma_f32 v[196:197], v[50:51], v[180:181], v[196:197] op_sel:[0,0,0] op_sel_hi:[1,0,1]
	v_pk_fma_f32 v[198:199], v[52:53], v[180:181], v[198:199] op_sel:[0,0,0] op_sel_hi:[1,0,1]
	ds_read_b128 v[50:53], v2 offset:59184
	s_waitcnt lgkmcnt(12)
	v_pk_fma_f32 v[200:201], v[208:209], v[180:181], v[200:201] op_sel:[0,0,0] op_sel_hi:[1,0,1]
	v_pk_fma_f32 v[202:203], v[210:211], v[180:181], v[202:203] op_sel:[0,0,0] op_sel_hi:[1,0,1]
	ds_read_b128 v[208:211], v2 offset:59200
	s_waitcnt lgkmcnt(12)
	v_pk_fma_f32 v[204:205], v[212:213], v[180:181], v[204:205] op_sel:[0,0,0] op_sel_hi:[1,0,1]
	v_pk_fma_f32 v[206:207], v[214:215], v[180:181], v[206:207] op_sel:[0,0,0] op_sel_hi:[1,0,1]
	ds_read_b128 v[212:215], v2 offset:59216
	s_waitcnt lgkmcnt(12)
	v_pk_fma_f32 v[182:183], v[218:219], v[180:181], v[182:183] op_sel:[0,1,0] op_sel_hi:[1,1,1]
	v_cvt_pk_bf16_f32 v232, v181, v2
	ds_write_b16 v108, v232 offset:32976
	ds_read_b128 v[216:219], v2 offset:59232
	s_waitcnt lgkmcnt(13)
	v_pk_fma_f32 v[184:185], v[220:221], v[180:181], v[184:185] op_sel:[0,1,0] op_sel_hi:[1,1,1]
	v_pk_fma_f32 v[186:187], v[222:223], v[180:181], v[186:187] op_sel:[0,1,0] op_sel_hi:[1,1,1]
	ds_read_b128 v[220:223], v2 offset:59248
	s_waitcnt lgkmcnt(13)
	v_pk_fma_f32 v[188:189], v[224:225], v[180:181], v[188:189] op_sel:[0,1,0] op_sel_hi:[1,1,1]
	v_pk_fma_f32 v[190:191], v[226:227], v[180:181], v[190:191] op_sel:[0,1,0] op_sel_hi:[1,1,1]
	ds_read_b128 v[224:227], v2 offset:59296
	s_waitcnt lgkmcnt(13)
	v_pk_fma_f32 v[192:193], v[228:229], v[180:181], v[192:193] op_sel:[0,1,0] op_sel_hi:[1,1,1]
	v_pk_fma_f32 v[194:195], v[230:231], v[180:181], v[194:195] op_sel:[0,1,0] op_sel_hi:[1,1,1]
	ds_read_b128 v[228:231], v2 offset:59312
	s_waitcnt lgkmcnt(13)
	v_pk_fma_f32 v[196:197], v[240:241], v[180:181], v[196:197] op_sel:[0,1,0] op_sel_hi:[1,1,1]
	v_pk_fma_f32 v[198:199], v[242:243], v[180:181], v[198:199] op_sel:[0,1,0] op_sel_hi:[1,1,1]
	ds_read_b128 v[240:243], v2 offset:59328
	s_waitcnt lgkmcnt(12)
	v_pk_fma_f32 v[200:201], v[244:245], v[180:181], v[200:201] op_sel:[0,1,0] op_sel_hi:[1,1,1]
	v_pk_fma_f32 v[202:203], v[246:247], v[180:181], v[202:203] op_sel:[0,1,0] op_sel_hi:[1,1,1]
	ds_read_b128 v[244:247], v2 offset:59344
	s_waitcnt lgkmcnt(12)
	v_pk_fma_f32 v[204:205], v[38:39], v[180:181], v[204:205] op_sel:[0,1,0] op_sel_hi:[1,1,1]
	v_pk_fma_f32 v[206:207], v[40:41], v[180:181], v[206:207] op_sel:[0,1,0] op_sel_hi:[1,1,1]
	ds_read_b128 v[38:41], v2 offset:59360
	s_waitcnt lgkmcnt(12)
	v_pk_fma_f32 v[182:183], v[44:45], v[182:183], v[182:183] op_sel:[0,0,0] op_sel_hi:[1,0,1]
	v_cvt_pk_bf16_f32 v233, v182, v2
	ds_write_b16 v108, v233 offset:33120
	ds_read_b128 v[42:45], v2 offset:59376
	s_waitcnt lgkmcnt(13)
	v_pk_fma_f32 v[184:185], v[46:47], v[182:183], v[184:185] op_sel:[0,0,0] op_sel_hi:[1,0,1]
	v_pk_fma_f32 v[186:187], v[48:49], v[182:183], v[186:187] op_sel:[0,0,0] op_sel_hi:[1,0,1]
	ds_read_b128 v[46:49], v2 offset:59424
	s_waitcnt lgkmcnt(13)
	v_pk_fma_f32 v[188:189], v[50:51], v[182:183], v[188:189] op_sel:[0,0,0] op_sel_hi:[1,0,1]
	v_pk_fma_f32 v[190:191], v[52:53], v[182:183], v[190:191] op_sel:[0,0,0] op_sel_hi:[1,0,1]
	ds_read_b128 v[50:53], v2 offset:59440
	s_waitcnt lgkmcnt(13)
	v_pk_fma_f32 v[192:193], v[208:209], v[182:183], v[192:193] op_sel:[0,0,0] op_sel_hi:[1,0,1]
	v_pk_fma_f32 v[194:195], v[210:211], v[182:183], v[194:195] op_sel:[0,0,0] op_sel_hi:[1,0,1]
	ds_read_b128 v[208:211], v2 offset:59456
	s_waitcnt lgkmcnt(13)
	v_pk_fma_f32 v[196:197], v[212:213], v[182:183], v[196:197] op_sel:[0,0,0] op_sel_hi:[1,0,1]
	v_pk_fma_f32 v[198:199], v[214:215], v[182:183], v[198:199] op_sel:[0,0,0] op_sel_hi:[1,0,1]
	ds_read_b128 v[212:215], v2 offset:59472
	s_waitcnt lgkmcnt(12)
	v_pk_fma_f32 v[200:201], v[216:217], v[182:183], v[200:201] op_sel:[0,0,0] op_sel_hi:[1,0,1]
	v_pk_fma_f32 v[202:203], v[218:219], v[182:183], v[202:203] op_sel:[0,0,0] op_sel_hi:[1,0,1]
	ds_read_b128 v[216:219], v2 offset:59488
	s_waitcnt lgkmcnt(12)
	v_pk_fma_f32 v[204:205], v[220:221], v[182:183], v[204:205] op_sel:[0,0,0] op_sel_hi:[1,0,1]
	v_pk_fma_f32 v[206:207], v[222:223], v[182:183], v[206:207] op_sel:[0,0,0] op_sel_hi:[1,0,1]
	ds_read_b128 v[220:223], v2 offset:59504
	s_waitcnt lgkmcnt(12)
	v_pk_fma_f32 v[184:185], v[224:225], v[182:183], v[184:185] op_sel:[0,1,0] op_sel_hi:[1,1,1]
	v_pk_fma_f32 v[186:187], v[226:227], v[182:183], v[186:187] op_sel:[0,1,0] op_sel_hi:[1,1,1]
	v_cvt_pk_bf16_f32 v248, v183, v2
	ds_write_b16 v108, v248 offset:33264
	ds_read_b128 v[224:227], v2 offset:59552
	s_waitcnt lgkmcnt(13)
	v_pk_fma_f32 v[188:189], v[228:229], v[182:183], v[188:189] op_sel:[0,1,0] op_sel_hi:[1,1,1]
	v_pk_fma_f32 v[190:191], v[230:231], v[182:183], v[190:191] op_sel:[0,1,0] op_sel_hi:[1,1,1]
	ds_read_b128 v[228:231], v2 offset:59568
	s_waitcnt lgkmcnt(13)
	v_pk_fma_f32 v[192:193], v[240:241], v[182:183], v[192:193] op_sel:[0,1,0] op_sel_hi:[1,1,1]
	v_pk_fma_f32 v[194:195], v[242:243], v[182:183], v[194:195] op_sel:[0,1,0] op_sel_hi:[1,1,1]
	ds_read_b128 v[240:243], v2 offset:59584
	s_waitcnt lgkmcnt(13)
	v_pk_fma_f32 v[196:197], v[244:245], v[182:183], v[196:197] op_sel:[0,1,0] op_sel_hi:[1,1,1]
	v_pk_fma_f32 v[198:199], v[246:247], v[182:183], v[198:199] op_sel:[0,1,0] op_sel_hi:[1,1,1]
	ds_read_b128 v[244:247], v2 offset:59600
	s_waitcnt lgkmcnt(13)
	v_pk_fma_f32 v[200:201], v[38:39], v[182:183], v[200:201] op_sel:[0,1,0] op_sel_hi:[1,1,1]
	v_pk_fma_f32 v[202:203], v[40:41], v[182:183], v[202:203] op_sel:[0,1,0] op_sel_hi:[1,1,1]
	ds_read_b128 v[38:41], v2 offset:59616
	s_waitcnt lgkmcnt(12)
	v_pk_fma_f32 v[204:205], v[42:43], v[182:183], v[204:205] op_sel:[0,1,0] op_sel_hi:[1,1,1]
	v_pk_fma_f32 v[206:207], v[44:45], v[182:183], v[206:207] op_sel:[0,1,0] op_sel_hi:[1,1,1]
	ds_read_b128 v[42:45], v2 offset:59632
	s_waitcnt lgkmcnt(12)
	v_pk_fma_f32 v[184:185], v[46:47], v[184:185], v[184:185] op_sel:[0,0,0] op_sel_hi:[1,0,1]
	v_pk_fma_f32 v[186:187], v[48:49], v[184:185], v[186:187] op_sel:[0,0,0] op_sel_hi:[1,0,1]
	v_cvt_pk_bf16_f32 v3, v184, v2
	ds_write_b16 v108, v3 offset:33408
	ds_read_b128 v[46:49], v2 offset:59680
	s_waitcnt lgkmcnt(13)
	v_pk_fma_f32 v[188:189], v[50:51], v[184:185], v[188:189] op_sel:[0,0,0] op_sel_hi:[1,0,1]
	v_pk_fma_f32 v[190:191], v[52:53], v[184:185], v[190:191] op_sel:[0,0,0] op_sel_hi:[1,0,1]
	ds_read_b128 v[50:53], v2 offset:59696
	s_waitcnt lgkmcnt(13)
	v_pk_fma_f32 v[192:193], v[208:209], v[184:185], v[192:193] op_sel:[0,0,0] op_sel_hi:[1,0,1]
	v_pk_fma_f32 v[194:195], v[210:211], v[184:185], v[194:195] op_sel:[0,0,0] op_sel_hi:[1,0,1]
	ds_read_b128 v[208:211], v2 offset:59712
	s_waitcnt lgkmcnt(13)
	v_pk_fma_f32 v[196:197], v[212:213], v[184:185], v[196:197] op_sel:[0,0,0] op_sel_hi:[1,0,1]
	v_pk_fma_f32 v[198:199], v[214:215], v[184:185], v[198:199] op_sel:[0,0,0] op_sel_hi:[1,0,1]
	ds_read_b128 v[212:215], v2 offset:59728
	s_waitcnt lgkmcnt(13)
	v_pk_fma_f32 v[200:201], v[216:217], v[184:185], v[200:201] op_sel:[0,0,0] op_sel_hi:[1,0,1]
	v_pk_fma_f32 v[202:203], v[218:219], v[184:185], v[202:203] op_sel:[0,0,0] op_sel_hi:[1,0,1]
	ds_read_b128 v[216:219], v2 offset:59744
	s_waitcnt lgkmcnt(13)
	v_pk_fma_f32 v[204:205], v[220:221], v[184:185], v[204:205] op_sel:[0,0,0] op_sel_hi:[1,0,1]
	v_pk_fma_f32 v[206:207], v[222:223], v[184:185], v[206:207] op_sel:[0,0,0] op_sel_hi:[1,0,1]
	ds_read_b128 v[220:223], v2 offset:59760
	s_waitcnt lgkmcnt(12)
	v_pk_fma_f32 v[186:187], v[226:227], v[184:185], v[186:187] op_sel:[0,1,0] op_sel_hi:[1,1,1]
	v_cvt_pk_bf16_f32 v232, v185, v2
	ds_write_b16 v108, v232 offset:33552
	ds_read_b128 v[224:227], v2 offset:59824
	s_waitcnt lgkmcnt(13)
	v_pk_fma_f32 v[188:189], v[228:229], v[184:185], v[188:189] op_sel:[0,1,0] op_sel_hi:[1,1,1]
	v_pk_fma_f32 v[190:191], v[230:231], v[184:185], v[190:191] op_sel:[0,1,0] op_sel_hi:[1,1,1]
	ds_read_b128 v[228:231], v2 offset:59840
	s_waitcnt lgkmcnt(13)
	v_pk_fma_f32 v[192:193], v[240:241], v[184:185], v[192:193] op_sel:[0,1,0] op_sel_hi:[1,1,1]
	v_pk_fma_f32 v[194:195], v[242:243], v[184:185], v[194:195] op_sel:[0,1,0] op_sel_hi:[1,1,1]
	ds_read_b128 v[240:243], v2 offset:59856
	s_waitcnt lgkmcnt(13)
	v_pk_fma_f32 v[196:197], v[244:245], v[184:185], v[196:197] op_sel:[0,1,0] op_sel_hi:[1,1,1]
	v_pk_fma_f32 v[198:199], v[246:247], v[184:185], v[198:199] op_sel:[0,1,0] op_sel_hi:[1,1,1]
	ds_read_b128 v[244:247], v2 offset:59872
	s_waitcnt lgkmcnt(13)
	v_pk_fma_f32 v[200:201], v[38:39], v[184:185], v[200:201] op_sel:[0,1,0] op_sel_hi:[1,1,1]
	v_pk_fma_f32 v[202:203], v[40:41], v[184:185], v[202:203] op_sel:[0,1,0] op_sel_hi:[1,1,1]
	ds_read_b128 v[38:41], v2 offset:59888
	s_waitcnt lgkmcnt(13)
	v_pk_fma_f32 v[204:205], v[42:43], v[184:185], v[204:205] op_sel:[0,1,0] op_sel_hi:[1,1,1]
	v_pk_fma_f32 v[206:207], v[44:45], v[184:185], v[206:207] op_sel:[0,1,0] op_sel_hi:[1,1,1]
	ds_read_b128 v[42:45], v2 offset:59952
	s_waitcnt lgkmcnt(12)
	v_pk_fma_f32 v[186:187], v[48:49], v[186:187], v[186:187] op_sel:[0,0,0] op_sel_hi:[1,0,1]
	v_cvt_pk_bf16_f32 v233, v186, v2
	ds_write_b16 v108, v233 offset:33696
	ds_read_b128 v[46:49], v2 offset:59968
	s_waitcnt lgkmcnt(13)
	v_pk_fma_f32 v[188:189], v[50:51], v[186:187], v[188:189] op_sel:[0,0,0] op_sel_hi:[1,0,1]
	v_pk_fma_f32 v[190:191], v[52:53], v[186:187], v[190:191] op_sel:[0,0,0] op_sel_hi:[1,0,1]
	ds_read_b128 v[50:53], v2 offset:59984
	s_waitcnt lgkmcnt(13)
	v_pk_fma_f32 v[192:193], v[208:209], v[186:187], v[192:193] op_sel:[0,0,0] op_sel_hi:[1,0,1]
	v_pk_fma_f32 v[194:195], v[210:211], v[186:187], v[194:195] op_sel:[0,0,0] op_sel_hi:[1,0,1]
	ds_read_b128 v[208:211], v2 offset:60000
	s_waitcnt lgkmcnt(13)
	v_pk_fma_f32 v[196:197], v[212:213], v[186:187], v[196:197] op_sel:[0,0,0] op_sel_hi:[1,0,1]
	v_pk_fma_f32 v[198:199], v[214:215], v[186:187], v[198:199] op_sel:[0,0,0] op_sel_hi:[1,0,1]
	ds_read_b128 v[212:215], v2 offset:60016
	s_waitcnt lgkmcnt(13)
	v_pk_fma_f32 v[200:201], v[216:217], v[186:187], v[200:201] op_sel:[0,0,0] op_sel_hi:[1,0,1]
	v_pk_fma_f32 v[202:203], v[218:219], v[186:187], v[202:203] op_sel:[0,0,0] op_sel_hi:[1,0,1]
	ds_read_b128 v[216:219], v2 offset:60080
	s_waitcnt lgkmcnt(13)
	v_pk_fma_f32 v[204:205], v[220:221], v[186:187], v[204:205] op_sel:[0,0,0] op_sel_hi:[1,0,1]
	v_pk_fma_f32 v[206:207], v[222:223], v[186:187], v[206:207] op_sel:[0,0,0] op_sel_hi:[1,0,1]
	ds_read_b128 v[220:223], v2 offset:60096
	s_waitcnt lgkmcnt(12)
	v_pk_fma_f32 v[188:189], v[224:225], v[186:187], v[188:189] op_sel:[0,1,0] op_sel_hi:[1,1,1]
	v_pk_fma_f32 v[190:191], v[226:227], v[186:187], v[190:191] op_sel:[0,1,0] op_sel_hi:[1,1,1]
	v_cvt_pk_bf16_f32 v248, v187, v2
	ds_write_b16 v108, v248 offset:33840
	ds_read_b128 v[224:227], v2 offset:60112
	s_waitcnt lgkmcnt(13)
	v_pk_fma_f32 v[192:193], v[228:229], v[186:187], v[192:193] op_sel:[0,1,0] op_sel_hi:[1,1,1]
	v_pk_fma_f32 v[194:195], v[230:231], v[186:187], v[194:195] op_sel:[0,1,0] op_sel_hi:[1,1,1]
	ds_read_b128 v[228:231], v2 offset:60128
	s_waitcnt lgkmcnt(13)
	v_pk_fma_f32 v[196:197], v[240:241], v[186:187], v[196:197] op_sel:[0,1,0] op_sel_hi:[1,1,1]
	v_pk_fma_f32 v[198:199], v[242:243], v[186:187], v[198:199] op_sel:[0,1,0] op_sel_hi:[1,1,1]
	ds_read_b128 v[240:243], v2 offset:60144
	s_waitcnt lgkmcnt(13)
	v_pk_fma_f32 v[200:201], v[244:245], v[186:187], v[200:201] op_sel:[0,1,0] op_sel_hi:[1,1,1]
	v_pk_fma_f32 v[202:203], v[246:247], v[186:187], v[202:203] op_sel:[0,1,0] op_sel_hi:[1,1,1]
	ds_read_b128 v[244:247], v2 offset:60208
	s_waitcnt lgkmcnt(13)
	v_pk_fma_f32 v[204:205], v[38:39], v[186:187], v[204:205] op_sel:[0,1,0] op_sel_hi:[1,1,1]
	v_pk_fma_f32 v[206:207], v[40:41], v[186:187], v[206:207] op_sel:[0,1,0] op_sel_hi:[1,1,1]
	ds_read_b128 v[38:41], v2 offset:60224
	s_waitcnt lgkmcnt(13)
	v_pk_fma_f32 v[188:189], v[42:43], v[188:189], v[188:189] op_sel:[0,0,0] op_sel_hi:[1,0,1]
	v_pk_fma_f32 v[190:191], v[44:45], v[188:189], v[190:191] op_sel:[0,0,0] op_sel_hi:[1,0,1]
	v_cvt_pk_bf16_f32 v3, v188, v2
	ds_write_b16 v108, v3 offset:33984
	ds_read_b128 v[42:45], v2 offset:60240
	s_waitcnt lgkmcnt(13)
	v_pk_fma_f32 v[192:193], v[46:47], v[188:189], v[192:193] op_sel:[0,0,0] op_sel_hi:[1,0,1]
	v_pk_fma_f32 v[194:195], v[48:49], v[188:189], v[194:195] op_sel:[0,0,0] op_sel_hi:[1,0,1]
	ds_read_b128 v[46:49], v2 offset:60256
	s_waitcnt lgkmcnt(13)
	v_pk_fma_f32 v[196:197], v[50:51], v[188:189], v[196:197] op_sel:[0,0,0] op_sel_hi:[1,0,1]
	v_pk_fma_f32 v[198:199], v[52:53], v[188:189], v[198:199] op_sel:[0,0,0] op_sel_hi:[1,0,1]
	ds_read_b128 v[50:53], v2 offset:60272
	s_waitcnt lgkmcnt(13)
	v_pk_fma_f32 v[200:201], v[208:209], v[188:189], v[200:201] op_sel:[0,0,0] op_sel_hi:[1,0,1]
	v_pk_fma_f32 v[202:203], v[210:211], v[188:189], v[202:203] op_sel:[0,0,0] op_sel_hi:[1,0,1]
	ds_read_b128 v[208:211], v2 offset:60352
	s_waitcnt lgkmcnt(13)
	v_pk_fma_f32 v[204:205], v[212:213], v[188:189], v[204:205] op_sel:[0,0,0] op_sel_hi:[1,0,1]
	v_pk_fma_f32 v[206:207], v[214:215], v[188:189], v[206:207] op_sel:[0,0,0] op_sel_hi:[1,0,1]
	ds_read_b128 v[212:215], v2 offset:60368
	s_waitcnt lgkmcnt(13)
	v_pk_fma_f32 v[190:191], v[218:219], v[188:189], v[190:191] op_sel:[0,1,0] op_sel_hi:[1,1,1]
	v_cvt_pk_bf16_f32 v232, v189, v2
	ds_write_b16 v108, v232 offset:34128
	ds_read_b128 v[216:219], v2 offset:60384
	s_waitcnt lgkmcnt(14)
	v_pk_fma_f32 v[192:193], v[220:221], v[188:189], v[192:193] op_sel:[0,1,0] op_sel_hi:[1,1,1]
	v_pk_fma_f32 v[194:195], v[222:223], v[188:189], v[194:195] op_sel:[0,1,0] op_sel_hi:[1,1,1]
	ds_read_b128 v[220:223], v2 offset:60400
	s_waitcnt lgkmcnt(13)
	v_pk_fma_f32 v[196:197], v[224:225], v[188:189], v[196:197] op_sel:[0,1,0] op_sel_hi:[1,1,1]
	v_pk_fma_f32 v[198:199], v[226:227], v[188:189], v[198:199] op_sel:[0,1,0] op_sel_hi:[1,1,1]
	ds_read_b128 v[224:227], v2 offset:60480
	s_waitcnt lgkmcnt(13)
	v_pk_fma_f32 v[200:201], v[228:229], v[188:189], v[200:201] op_sel:[0,1,0] op_sel_hi:[1,1,1]
	v_pk_fma_f32 v[202:203], v[230:231], v[188:189], v[202:203] op_sel:[0,1,0] op_sel_hi:[1,1,1]
	ds_read_b128 v[228:231], v2 offset:60496
	s_waitcnt lgkmcnt(13)
	v_pk_fma_f32 v[204:205], v[240:241], v[188:189], v[204:205] op_sel:[0,1,0] op_sel_hi:[1,1,1]
	v_pk_fma_f32 v[206:207], v[242:243], v[188:189], v[206:207] op_sel:[0,1,0] op_sel_hi:[1,1,1]
	ds_read_b128 v[240:243], v2 offset:60512
	s_waitcnt lgkmcnt(13)
	v_pk_fma_f32 v[190:191], v[246:247], v[190:191], v[190:191] op_sel:[0,0,0] op_sel_hi:[1,0,1]
	v_cvt_pk_bf16_f32 v233, v190, v2
	ds_write_b16 v108, v233 offset:34272
	ds_read_b128 v[244:247], v2 offset:60528
	s_waitcnt lgkmcnt(14)
	v_pk_fma_f32 v[192:193], v[38:39], v[190:191], v[192:193] op_sel:[0,0,0] op_sel_hi:[1,0,1]
	v_pk_fma_f32 v[194:195], v[40:41], v[190:191], v[194:195] op_sel:[0,0,0] op_sel_hi:[1,0,1]
	ds_read_b128 v[38:41], v2 offset:60608
	s_waitcnt lgkmcnt(13)
	v_pk_fma_f32 v[196:197], v[42:43], v[190:191], v[196:197] op_sel:[0,0,0] op_sel_hi:[1,0,1]
	v_pk_fma_f32 v[198:199], v[44:45], v[190:191], v[198:199] op_sel:[0,0,0] op_sel_hi:[1,0,1]
	ds_read_b128 v[42:45], v2 offset:60624
	s_waitcnt lgkmcnt(13)
	v_pk_fma_f32 v[200:201], v[46:47], v[190:191], v[200:201] op_sel:[0,0,0] op_sel_hi:[1,0,1]
	v_pk_fma_f32 v[202:203], v[48:49], v[190:191], v[202:203] op_sel:[0,0,0] op_sel_hi:[1,0,1]
	ds_read_b128 v[46:49], v2 offset:60640
	s_waitcnt lgkmcnt(13)
	v_pk_fma_f32 v[204:205], v[50:51], v[190:191], v[204:205] op_sel:[0,0,0] op_sel_hi:[1,0,1]
	v_pk_fma_f32 v[206:207], v[52:53], v[190:191], v[206:207] op_sel:[0,0,0] op_sel_hi:[1,0,1]
	ds_read_b128 v[50:53], v2 offset:60656
	s_waitcnt lgkmcnt(13)
	v_pk_fma_f32 v[192:193], v[208:209], v[190:191], v[192:193] op_sel:[0,1,0] op_sel_hi:[1,1,1]
	v_pk_fma_f32 v[194:195], v[210:211], v[190:191], v[194:195] op_sel:[0,1,0] op_sel_hi:[1,1,1]
	v_cvt_pk_bf16_f32 v248, v191, v2
	ds_write_b16 v108, v248 offset:34416
	ds_read_b128 v[208:211], v2 offset:60736
	s_waitcnt lgkmcnt(14)
	v_pk_fma_f32 v[196:197], v[212:213], v[190:191], v[196:197] op_sel:[0,1,0] op_sel_hi:[1,1,1]
	v_pk_fma_f32 v[198:199], v[214:215], v[190:191], v[198:199] op_sel:[0,1,0] op_sel_hi:[1,1,1]
	ds_read_b128 v[212:215], v2 offset:60752
	s_waitcnt lgkmcnt(13)
	v_pk_fma_f32 v[200:201], v[216:217], v[190:191], v[200:201] op_sel:[0,1,0] op_sel_hi:[1,1,1]
	v_pk_fma_f32 v[202:203], v[218:219], v[190:191], v[202:203] op_sel:[0,1,0] op_sel_hi:[1,1,1]
	ds_read_b128 v[216:219], v2 offset:60768
	s_waitcnt lgkmcnt(13)
	v_pk_fma_f32 v[204:205], v[220:221], v[190:191], v[204:205] op_sel:[0,1,0] op_sel_hi:[1,1,1]
	v_pk_fma_f32 v[206:207], v[222:223], v[190:191], v[206:207] op_sel:[0,1,0] op_sel_hi:[1,1,1]
	ds_read_b128 v[220:223], v2 offset:60784
	s_waitcnt lgkmcnt(13)
	v_pk_fma_f32 v[192:193], v[224:225], v[192:193], v[192:193] op_sel:[0,0,0] op_sel_hi:[1,0,1]
	v_pk_fma_f32 v[194:195], v[226:227], v[192:193], v[194:195] op_sel:[0,0,0] op_sel_hi:[1,0,1]
	v_cvt_pk_bf16_f32 v3, v192, v2
	ds_write_b16 v108, v3 offset:34560
	ds_read_b128 v[224:227], v2 offset:60880
	s_waitcnt lgkmcnt(14)
	v_pk_fma_f32 v[196:197], v[228:229], v[192:193], v[196:197] op_sel:[0,0,0] op_sel_hi:[1,0,1]
	v_pk_fma_f32 v[198:199], v[230:231], v[192:193], v[198:199] op_sel:[0,0,0] op_sel_hi:[1,0,1]
	ds_read_b128 v[228:231], v2 offset:60896
	s_waitcnt lgkmcnt(14)
	v_pk_fma_f32 v[200:201], v[240:241], v[192:193], v[200:201] op_sel:[0,0,0] op_sel_hi:[1,0,1]
	v_pk_fma_f32 v[202:203], v[242:243], v[192:193], v[202:203] op_sel:[0,0,0] op_sel_hi:[1,0,1]
	ds_read_b128 v[240:243], v2 offset:60912
	s_waitcnt lgkmcnt(13)
	v_pk_fma_f32 v[204:205], v[244:245], v[192:193], v[204:205] op_sel:[0,0,0] op_sel_hi:[1,0,1]
	v_pk_fma_f32 v[206:207], v[246:247], v[192:193], v[206:207] op_sel:[0,0,0] op_sel_hi:[1,0,1]
	ds_read_b128 v[244:247], v2 offset:61008
	s_waitcnt lgkmcnt(13)
	v_pk_fma_f32 v[194:195], v[40:41], v[192:193], v[194:195] op_sel:[0,1,0] op_sel_hi:[1,1,1]
	v_cvt_pk_bf16_f32 v232, v193, v2
	ds_write_b16 v108, v232 offset:34704
	ds_read_b128 v[38:41], v2 offset:61024
	s_waitcnt lgkmcnt(14)
	v_pk_fma_f32 v[196:197], v[42:43], v[192:193], v[196:197] op_sel:[0,1,0] op_sel_hi:[1,1,1]
	v_pk_fma_f32 v[198:199], v[44:45], v[192:193], v[198:199] op_sel:[0,1,0] op_sel_hi:[1,1,1]
	ds_read_b128 v[42:45], v2 offset:61040
	s_waitcnt lgkmcnt(14)
	v_pk_fma_f32 v[200:201], v[46:47], v[192:193], v[200:201] op_sel:[0,1,0] op_sel_hi:[1,1,1]
	v_pk_fma_f32 v[202:203], v[48:49], v[192:193], v[202:203] op_sel:[0,1,0] op_sel_hi:[1,1,1]
	ds_read_b128 v[46:49], v2 offset:61136
	s_waitcnt lgkmcnt(14)
	v_pk_fma_f32 v[204:205], v[50:51], v[192:193], v[204:205] op_sel:[0,1,0] op_sel_hi:[1,1,1]
	v_pk_fma_f32 v[206:207], v[52:53], v[192:193], v[206:207] op_sel:[0,1,0] op_sel_hi:[1,1,1]
	ds_read_b128 v[50:53], v2 offset:61152
	s_waitcnt lgkmcnt(13)
	v_pk_fma_f32 v[194:195], v[210:211], v[194:195], v[194:195] op_sel:[0,0,0] op_sel_hi:[1,0,1]
	v_cvt_pk_bf16_f32 v233, v194, v2
	ds_write_b16 v108, v233 offset:34848
	ds_read_b128 v[208:211], v2 offset:61168
	s_waitcnt lgkmcnt(14)
	v_pk_fma_f32 v[196:197], v[212:213], v[194:195], v[196:197] op_sel:[0,0,0] op_sel_hi:[1,0,1]
	v_pk_fma_f32 v[198:199], v[214:215], v[194:195], v[198:199] op_sel:[0,0,0] op_sel_hi:[1,0,1]
	ds_read_b128 v[212:215], v2 offset:61264
	s_waitcnt lgkmcnt(14)
	v_pk_fma_f32 v[200:201], v[216:217], v[194:195], v[200:201] op_sel:[0,0,0] op_sel_hi:[1,0,1]
	v_pk_fma_f32 v[202:203], v[218:219], v[194:195], v[202:203] op_sel:[0,0,0] op_sel_hi:[1,0,1]
	ds_read_b128 v[216:219], v2 offset:61280
	s_waitcnt lgkmcnt(14)
	v_pk_fma_f32 v[204:205], v[220:221], v[194:195], v[204:205] op_sel:[0,0,0] op_sel_hi:[1,0,1]
	v_pk_fma_f32 v[206:207], v[222:223], v[194:195], v[206:207] op_sel:[0,0,0] op_sel_hi:[1,0,1]
	ds_read_b128 v[220:223], v2 offset:61296
	s_waitcnt lgkmcnt(13)
	v_pk_fma_f32 v[196:197], v[224:225], v[194:195], v[196:197] op_sel:[0,1,0] op_sel_hi:[1,1,1]
	v_pk_fma_f32 v[198:199], v[226:227], v[194:195], v[198:199] op_sel:[0,1,0] op_sel_hi:[1,1,1]
	v_cvt_pk_bf16_f32 v248, v195, v2
	ds_write_b16 v108, v248 offset:34992
	ds_read_b128 v[224:227], v2 offset:61408
	s_waitcnt lgkmcnt(14)
	v_pk_fma_f32 v[200:201], v[228:229], v[194:195], v[200:201] op_sel:[0,1,0] op_sel_hi:[1,1,1]
	v_pk_fma_f32 v[202:203], v[230:231], v[194:195], v[202:203] op_sel:[0,1,0] op_sel_hi:[1,1,1]
	ds_read_b128 v[228:231], v2 offset:61424
	s_waitcnt lgkmcnt(14)
	v_pk_fma_f32 v[204:205], v[240:241], v[194:195], v[204:205] op_sel:[0,1,0] op_sel_hi:[1,1,1]
	v_pk_fma_f32 v[206:207], v[242:243], v[194:195], v[206:207] op_sel:[0,1,0] op_sel_hi:[1,1,1]
	ds_read_b128 v[240:243], v2 offset:61536
	s_waitcnt lgkmcnt(14)
	v_pk_fma_f32 v[196:197], v[244:245], v[196:197], v[196:197] op_sel:[0,0,0] op_sel_hi:[1,0,1]
	v_pk_fma_f32 v[198:199], v[246:247], v[196:197], v[198:199] op_sel:[0,0,0] op_sel_hi:[1,0,1]
	v_cvt_pk_bf16_f32 v3, v196, v2
	ds_write_b16 v108, v3 offset:35136
	s_waitcnt lgkmcnt(14)
	ds_read_b128 v[244:247], v2 offset:61552
	s_waitcnt lgkmcnt(14)
	v_pk_fma_f32 v[200:201], v[38:39], v[196:197], v[200:201] op_sel:[0,0,0] op_sel_hi:[1,0,1]
	v_pk_fma_f32 v[202:203], v[40:41], v[196:197], v[202:203] op_sel:[0,0,0] op_sel_hi:[1,0,1]
	ds_read_b128 v[38:41], v2 offset:61664
	s_waitcnt lgkmcnt(14)
	v_pk_fma_f32 v[204:205], v[42:43], v[196:197], v[204:205] op_sel:[0,0,0] op_sel_hi:[1,0,1]
	v_pk_fma_f32 v[206:207], v[44:45], v[196:197], v[206:207] op_sel:[0,0,0] op_sel_hi:[1,0,1]
	ds_read_b128 v[42:45], v2 offset:61680
	s_waitcnt lgkmcnt(14)
	v_pk_fma_f32 v[198:199], v[48:49], v[196:197], v[198:199] op_sel:[0,1,0] op_sel_hi:[1,1,1]
	v_cvt_pk_bf16_f32 v232, v197, v2
	ds_write_b16 v108, v232 offset:35280
	s_waitcnt lgkmcnt(14)
	ds_read_b128 v[46:49], v2 offset:61792
	v_pk_fma_f32 v[200:201], v[50:51], v[196:197], v[200:201] op_sel:[0,1,0] op_sel_hi:[1,1,1]
	v_pk_fma_f32 v[202:203], v[52:53], v[196:197], v[202:203] op_sel:[0,1,0] op_sel_hi:[1,1,1]
	s_waitcnt lgkmcnt(14)
	ds_read_b128 v[50:53], v2 offset:61808
	s_waitcnt lgkmcnt(14)
	v_pk_fma_f32 v[204:205], v[208:209], v[196:197], v[204:205] op_sel:[0,1,0] op_sel_hi:[1,1,1]
	v_pk_fma_f32 v[206:207], v[210:211], v[196:197], v[206:207] op_sel:[0,1,0] op_sel_hi:[1,1,1]
	ds_read_b128 v[208:211], v2 offset:61936
	s_waitcnt lgkmcnt(14)
	v_pk_fma_f32 v[198:199], v[214:215], v[198:199], v[198:199] op_sel:[0,0,0] op_sel_hi:[1,0,1]
	v_cvt_pk_bf16_f32 v233, v198, v2
	ds_write_b16 v108, v233 offset:35424
	s_waitcnt lgkmcnt(14)
	ds_read_b128 v[212:215], v2 offset:62064
	v_pk_fma_f32 v[200:201], v[216:217], v[198:199], v[200:201] op_sel:[0,0,0] op_sel_hi:[1,0,1]
	v_pk_fma_f32 v[202:203], v[218:219], v[198:199], v[202:203] op_sel:[0,0,0] op_sel_hi:[1,0,1]
	s_waitcnt lgkmcnt(14)
	ds_read_b128 v[216:219], v2 offset:62192
	v_pk_fma_f32 v[204:205], v[220:221], v[198:199], v[204:205] op_sel:[0,0,0] op_sel_hi:[1,0,1]
	v_pk_fma_f32 v[206:207], v[222:223], v[198:199], v[206:207] op_sel:[0,0,0] op_sel_hi:[1,0,1]
	s_waitcnt lgkmcnt(14)
	ds_read_b128 v[220:223], v2 offset:62320
	s_waitcnt lgkmcnt(14)
	v_pk_fma_f32 v[200:201], v[224:225], v[198:199], v[200:201] op_sel:[0,1,0] op_sel_hi:[1,1,1]
	v_pk_fma_f32 v[202:203], v[226:227], v[198:199], v[202:203] op_sel:[0,1,0] op_sel_hi:[1,1,1]
	v_cvt_pk_bf16_f32 v248, v199, v2
	ds_write_b16 v108, v248 offset:35568
	s_waitcnt lgkmcnt(14)
	v_pk_fma_f32 v[204:205], v[228:229], v[198:199], v[204:205] op_sel:[0,1,0] op_sel_hi:[1,1,1]
	v_pk_fma_f32 v[206:207], v[230:231], v[198:199], v[206:207] op_sel:[0,1,0] op_sel_hi:[1,1,1]
	s_waitcnt lgkmcnt(13)
	v_pk_fma_f32 v[200:201], v[240:241], v[200:201], v[200:201] op_sel:[0,0,0] op_sel_hi:[1,0,1]
	v_pk_fma_f32 v[202:203], v[242:243], v[200:201], v[202:203] op_sel:[0,0,0] op_sel_hi:[1,0,1]
	v_cvt_pk_bf16_f32 v3, v200, v2
	ds_write_b16 v108, v3 offset:35712
	s_waitcnt lgkmcnt(12)
	v_pk_fma_f32 v[204:205], v[244:245], v[200:201], v[204:205] op_sel:[0,0,0] op_sel_hi:[1,0,1]
	v_pk_fma_f32 v[206:207], v[246:247], v[200:201], v[206:207] op_sel:[0,0,0] op_sel_hi:[1,0,1]
	s_waitcnt lgkmcnt(11)
	v_pk_fma_f32 v[202:203], v[40:41], v[200:201], v[202:203] op_sel:[0,1,0] op_sel_hi:[1,1,1]
	v_cvt_pk_bf16_f32 v232, v201, v2
	ds_write_b16 v108, v232 offset:35856
	s_waitcnt lgkmcnt(11)
	v_pk_fma_f32 v[204:205], v[42:43], v[200:201], v[204:205] op_sel:[0,1,0] op_sel_hi:[1,1,1]
	v_pk_fma_f32 v[206:207], v[44:45], v[200:201], v[206:207] op_sel:[0,1,0] op_sel_hi:[1,1,1]
	s_waitcnt lgkmcnt(9)
	v_pk_fma_f32 v[202:203], v[48:49], v[202:203], v[202:203] op_sel:[0,0,0] op_sel_hi:[1,0,1]
	v_cvt_pk_bf16_f32 v233, v202, v2
	ds_write_b16 v108, v233 offset:36000
	s_waitcnt lgkmcnt(9)
	v_pk_fma_f32 v[204:205], v[50:51], v[202:203], v[204:205] op_sel:[0,0,0] op_sel_hi:[1,0,1]
	v_pk_fma_f32 v[206:207], v[52:53], v[202:203], v[206:207] op_sel:[0,0,0] op_sel_hi:[1,0,1]
	s_waitcnt lgkmcnt(8)
	v_pk_fma_f32 v[204:205], v[208:209], v[202:203], v[204:205] op_sel:[0,1,0] op_sel_hi:[1,1,1]
	v_pk_fma_f32 v[206:207], v[210:211], v[202:203], v[206:207] op_sel:[0,1,0] op_sel_hi:[1,1,1]
	v_cvt_pk_bf16_f32 v248, v203, v2
	ds_write_b16 v108, v248 offset:36144
	s_waitcnt lgkmcnt(7)
	v_pk_fma_f32 v[204:205], v[212:213], v[204:205], v[204:205] op_sel:[0,0,0] op_sel_hi:[1,0,1]
	v_pk_fma_f32 v[206:207], v[214:215], v[204:205], v[206:207] op_sel:[0,0,0] op_sel_hi:[1,0,1]
	v_cvt_pk_bf16_f32 v3, v204, v2
	ds_write_b16 v108, v3 offset:36288
	s_waitcnt lgkmcnt(7)
	v_pk_fma_f32 v[206:207], v[218:219], v[204:205], v[206:207] op_sel:[0,1,0] op_sel_hi:[1,1,1]
	v_cvt_pk_bf16_f32 v232, v205, v2
	ds_write_b16 v108, v232 offset:36432
	s_waitcnt lgkmcnt(7)
	v_pk_fma_f32 v[206:207], v[222:223], v[206:207], v[206:207] op_sel:[0,0,0] op_sel_hi:[1,0,1]
	v_cvt_pk_bf16_f32 v233, v206, v2
	ds_write_b16 v108, v233 offset:36576
	v_cvt_pk_bf16_f32 v248, v207, v2
	ds_write_b16 v108, v248 offset:36720

.LBB0_3366:
	s_cmp_eq_u32 s25, 0
	s_cselect_b64 s[34:35], -1, 0
	s_or_b64 s[34:35], s[8:9], s[34:35]
	s_and_b64 vcc, exec, s[34:35]
	s_and_b64 s[98:99], exec, s[30:31]
	s_cbranch_scc1 .Lnabpf_skip_1
	ds_read_b128 v[208:211], v2 offset:58368
	ds_read_b128 v[212:215], v2 offset:58384
	ds_read_b128 v[216:219], v2 offset:58400
	ds_read_b128 v[220:223], v2 offset:58416
	ds_read_b128 v[224:227], v2 offset:58432
	ds_read_b128 v[228:231], v2 offset:58448
	ds_read_b128 v[240:243], v2 offset:58464
	ds_read_b128 v[244:247], v2 offset:58480
	ds_read_b128 v[38:41], v2 offset:58496
	ds_read_b128 v[42:45], v2 offset:58512
	ds_read_b128 v[46:49], v2 offset:58528
	ds_read_b128 v[50:53], v2 offset:58544
.Lnabpf_skip_1:
	s_waitcnt lgkmcnt(0)
	s_barrier
	s_cbranch_vccnz .LBB0_3369
	v_cndmask_b32_e64 v3, 0, 1, s[62:63]
	s_add_i32 s25, s25, -1
	v_lshlrev_b32_e32 v3, 7, v3
	v_readlane_b32 s34, v252, 12
	s_bitcmp0_b32 s25, 0
	s_movk_i32 s25, 0x6c00
	v_add_u32_e32 v3, s34, v3
	s_cselect_b32 s25, s25, 0x13600
	s_cselect_b32 s34, s20, 0x14800
	v_add_u32_e32 v4, s34, v122
	v_add_u32_e32 v5, s25, v122
	v_mov_b32_e32 v38, v123
	s_mov_b32 s25, s39
	ds_read_b32 v208, v38
	ds_read_b32 v209, v3
	ds_read_u16 v210, v5
	ds_read_u16 v211, v4

.LBB0_3369:
	s_and_b64 vcc, exec, s[30:31]
	s_cbranch_vccnz .LBB0_3371
	ds_read2st64_b32 v[176:177], v111 offset0:244 offset1:245
	ds_read2st64_b32 v[178:179], v111 offset0:246 offset1:247
	ds_read2st64_b32 v[180:181], v111 offset0:248 offset1:249
	ds_read2st64_b32 v[182:183], v111 offset0:250 offset1:251
	ds_read2st64_b32 v[184:185], v111 offset0:252 offset1:253
	ds_read2st64_b32 v[186:187], v111 offset0:254 offset1:255
	ds_read2st64_b32 v[188:189], v112 offset0:12 offset1:13
	ds_read2st64_b32 v[190:191], v112 offset0:14 offset1:15
	ds_read2st64_b32 v[192:193], v112 offset0:16 offset1:17
	ds_read2st64_b32 v[194:195], v112 offset0:18 offset1:19
	ds_read2st64_b32 v[196:197], v112 offset0:20 offset1:21
	ds_read2st64_b32 v[198:199], v112 offset0:22 offset1:23
	ds_read2st64_b32 v[200:201], v112 offset0:24 offset1:25
	ds_read2st64_b32 v[202:203], v112 offset0:26 offset1:27
	ds_read2st64_b32 v[204:205], v112 offset0:28 offset1:29
	s_waitcnt lgkmcnt(14)
	ds_read2st64_b32 v[206:207], v112 offset0:30 offset1:31
	v_pk_fma_f32 v[176:177], v[208:209], v[176:177], v[176:177] op_sel:[0,0,0] op_sel_hi:[1,0,1]
	s_waitcnt lgkmcnt(14)
	v_pk_fma_f32 v[178:179], v[210:211], v[176:177], v[178:179] op_sel:[0,0,0] op_sel_hi:[1,0,1]
	v_cvt_pk_bf16_f32 v3, v176, v2
	ds_write_b16 v113, v3 offset:32256
	s_waitcnt lgkmcnt(14)
	ds_read_b128 v[208:211], v2 offset:58560
	v_pk_fma_f32 v[180:181], v[212:213], v[176:177], v[180:181] op_sel:[0,0,0] op_sel_hi:[1,0,1]
	s_waitcnt lgkmcnt(14)
	v_pk_fma_f32 v[182:183], v[214:215], v[176:177], v[182:183] op_sel:[0,0,0] op_sel_hi:[1,0,1]
	ds_read_b128 v[212:215], v2 offset:58576
	s_waitcnt lgkmcnt(14)
	v_pk_fma_f32 v[184:185], v[216:217], v[176:177], v[184:185] op_sel:[0,0,0] op_sel_hi:[1,0,1]
	s_waitcnt lgkmcnt(13)
	v_pk_fma_f32 v[186:187], v[218:219], v[176:177], v[186:187] op_sel:[0,0,0] op_sel_hi:[1,0,1]
	ds_read_b128 v[216:219], v2 offset:58592
	s_waitcnt lgkmcnt(13)
	v_pk_fma_f32 v[188:189], v[220:221], v[176:177], v[188:189] op_sel:[0,0,0] op_sel_hi:[1,0,1]
	s_waitcnt lgkmcnt(12)
	v_pk_fma_f32 v[190:191], v[222:223], v[176:177], v[190:191] op_sel:[0,0,0] op_sel_hi:[1,0,1]
	ds_read_b128 v[220:223], v2 offset:58608
	s_waitcnt lgkmcnt(12)
	v_pk_fma_f32 v[192:193], v[224:225], v[176:177], v[192:193] op_sel:[0,0,0] op_sel_hi:[1,0,1]
	s_waitcnt lgkmcnt(11)
	v_pk_fma_f32 v[194:195], v[226:227], v[176:177], v[194:195] op_sel:[0,0,0] op_sel_hi:[1,0,1]
	ds_read_b128 v[224:227], v2 offset:58624
	s_waitcnt lgkmcnt(11)
	v_pk_fma_f32 v[196:197], v[228:229], v[176:177], v[196:197] op_sel:[0,0,0] op_sel_hi:[1,0,1]
	s_waitcnt lgkmcnt(10)
	v_pk_fma_f32 v[198:199], v[230:231], v[176:177], v[198:199] op_sel:[0,0,0] op_sel_hi:[1,0,1]
	ds_read_b128 v[228:231], v2 offset:58640
	s_waitcnt lgkmcnt(10)
	v_pk_fma_f32 v[200:201], v[240:241], v[176:177], v[200:201] op_sel:[0,0,0] op_sel_hi:[1,0,1]
	s_waitcnt lgkmcnt(9)
	v_pk_fma_f32 v[202:203], v[242:243], v[176:177], v[202:203] op_sel:[0,0,0] op_sel_hi:[1,0,1]
	ds_read_b128 v[240:243], v2 offset:58656
	s_waitcnt lgkmcnt(9)
	v_pk_fma_f32 v[204:205], v[244:245], v[176:177], v[204:205] op_sel:[0,0,0] op_sel_hi:[1,0,1]
	s_waitcnt lgkmcnt(8)
	v_pk_fma_f32 v[206:207], v[246:247], v[176:177], v[206:207] op_sel:[0,0,0] op_sel_hi:[1,0,1]
	ds_read_b128 v[244:247], v2 offset:58672
	v_pk_fma_f32 v[178:179], v[40:41], v[176:177], v[178:179] op_sel:[0,1,0] op_sel_hi:[1,1,1]
	v_cvt_pk_bf16_f32 v232, v177, v2
	ds_write_b16 v113, v232 offset:32400
	ds_read_b128 v[38:41], v2 offset:58688
	v_pk_fma_f32 v[180:181], v[42:43], v[176:177], v[180:181] op_sel:[0,1,0] op_sel_hi:[1,1,1]
	v_pk_fma_f32 v[182:183], v[44:45], v[176:177], v[182:183] op_sel:[0,1,0] op_sel_hi:[1,1,1]
	ds_read_b128 v[42:45], v2 offset:58704
	v_pk_fma_f32 v[184:185], v[46:47], v[176:177], v[184:185] op_sel:[0,1,0] op_sel_hi:[1,1,1]
	v_pk_fma_f32 v[186:187], v[48:49], v[176:177], v[186:187] op_sel:[0,1,0] op_sel_hi:[1,1,1]
	ds_read_b128 v[46:49], v2 offset:58720
	v_pk_fma_f32 v[188:189], v[50:51], v[176:177], v[188:189] op_sel:[0,1,0] op_sel_hi:[1,1,1]
	v_pk_fma_f32 v[190:191], v[52:53], v[176:177], v[190:191] op_sel:[0,1,0] op_sel_hi:[1,1,1]
	ds_read_b128 v[50:53], v2 offset:58736
	s_waitcnt lgkmcnt(12)
	v_pk_fma_f32 v[192:193], v[208:209], v[176:177], v[192:193] op_sel:[0,1,0] op_sel_hi:[1,1,1]
	v_pk_fma_f32 v[194:195], v[210:211], v[176:177], v[194:195] op_sel:[0,1,0] op_sel_hi:[1,1,1]
	ds_read_b128 v[208:211], v2 offset:58768
	s_waitcnt lgkmcnt(12)
	v_pk_fma_f32 v[196:197], v[212:213], v[176:177], v[196:197] op_sel:[0,1,0] op_sel_hi:[1,1,1]
	v_pk_fma_f32 v[198:199], v[214:215], v[176:177], v[198:199] op_sel:[0,1,0] op_sel_hi:[1,1,1]
	ds_read_b128 v[212:215], v2 offset:58784
	s_waitcnt lgkmcnt(12)
	v_pk_fma_f32 v[200:201], v[216:217], v[176:177], v[200:201] op_sel:[0,1,0] op_sel_hi:[1,1,1]
	v_pk_fma_f32 v[202:203], v[218:219], v[176:177], v[202:203] op_sel:[0,1,0] op_sel_hi:[1,1,1]
	ds_read_b128 v[216:219], v2 offset:58800
	s_waitcnt lgkmcnt(12)
	v_pk_fma_f32 v[204:205], v[220:221], v[176:177], v[204:205] op_sel:[0,1,0] op_sel_hi:[1,1,1]
	v_pk_fma_f32 v[206:207], v[222:223], v[176:177], v[206:207] op_sel:[0,1,0] op_sel_hi:[1,1,1]
	ds_read_b128 v[220:223], v2 offset:58816
	s_waitcnt lgkmcnt(12)
	v_pk_fma_f32 v[178:179], v[226:227], v[178:179], v[178:179] op_sel:[0,0,0] op_sel_hi:[1,0,1]
	v_cvt_pk_bf16_f32 v233, v178, v2
	ds_write_b16 v113, v233 offset:32544
	ds_read_b128 v[224:227], v2 offset:58832
	s_waitcnt lgkmcnt(13)
	v_pk_fma_f32 v[180:181], v[228:229], v[178:179], v[180:181] op_sel:[0,0,0] op_sel_hi:[1,0,1]
	v_pk_fma_f32 v[182:183], v[230:231], v[178:179], v[182:183] op_sel:[0,0,0] op_sel_hi:[1,0,1]
	ds_read_b128 v[228:231], v2 offset:58848
	s_waitcnt lgkmcnt(13)
	v_pk_fma_f32 v[184:185], v[240:241], v[178:179], v[184:185] op_sel:[0,0,0] op_sel_hi:[1,0,1]
	v_pk_fma_f32 v[186:187], v[242:243], v[178:179], v[186:187] op_sel:[0,0,0] op_sel_hi:[1,0,1]
	ds_read_b128 v[240:243], v2 offset:58864
	s_waitcnt lgkmcnt(13)
	v_pk_fma_f32 v[188:189], v[244:245], v[178:179], v[188:189] op_sel:[0,0,0] op_sel_hi:[1,0,1]
	v_pk_fma_f32 v[190:191], v[246:247], v[178:179], v[190:191] op_sel:[0,0,0] op_sel_hi:[1,0,1]
	ds_read_b128 v[244:247], v2 offset:58896
	s_waitcnt lgkmcnt(12)
	v_pk_fma_f32 v[192:193], v[38:39], v[178:179], v[192:193] op_sel:[0,0,0] op_sel_hi:[1,0,1]
	v_pk_fma_f32 v[194:195], v[40:41], v[178:179], v[194:195] op_sel:[0,0,0] op_sel_hi:[1,0,1]
	ds_read_b128 v[38:41], v2 offset:58912
	s_waitcnt lgkmcnt(12)
	v_pk_fma_f32 v[196:197], v[42:43], v[178:179], v[196:197] op_sel:[0,0,0] op_sel_hi:[1,0,1]
	v_pk_fma_f32 v[198:199], v[44:45], v[178:179], v[198:199] op_sel:[0,0,0] op_sel_hi:[1,0,1]
	ds_read_b128 v[42:45], v2 offset:58928
	s_waitcnt lgkmcnt(12)
	v_pk_fma_f32 v[200:201], v[46:47], v[178:179], v[200:201] op_sel:[0,0,0] op_sel_hi:[1,0,1]
	v_pk_fma_f32 v[202:203], v[48:49], v[178:179], v[202:203] op_sel:[0,0,0] op_sel_hi:[1,0,1]
	ds_read_b128 v[46:49], v2 offset:58944
	s_waitcnt lgkmcnt(12)
	v_pk_fma_f32 v[204:205], v[50:51], v[178:179], v[204:205] op_sel:[0,0,0] op_sel_hi:[1,0,1]
	v_pk_fma_f32 v[206:207], v[52:53], v[178:179], v[206:207] op_sel:[0,0,0] op_sel_hi:[1,0,1]
	ds_read_b128 v[50:53], v2 offset:58960
	s_waitcnt lgkmcnt(12)
	v_pk_fma_f32 v[180:181], v[208:209], v[178:179], v[180:181] op_sel:[0,1,0] op_sel_hi:[1,1,1]
	v_pk_fma_f32 v[182:183], v[210:211], v[178:179], v[182:183] op_sel:[0,1,0] op_sel_hi:[1,1,1]
	v_cvt_pk_bf16_f32 v248, v179, v2
	ds_write_b16 v113, v248 offset:32688
	ds_read_b128 v[208:211], v2 offset:58976
	s_waitcnt lgkmcnt(13)
	v_pk_fma_f32 v[184:185], v[212:213], v[178:179], v[184:185] op_sel:[0,1,0] op_sel_hi:[1,1,1]
	v_pk_fma_f32 v[186:187], v[214:215], v[178:179], v[186:187] op_sel:[0,1,0] op_sel_hi:[1,1,1]
	ds_read_b128 v[212:215], v2 offset:58992
	s_waitcnt lgkmcnt(13)
	v_pk_fma_f32 v[188:189], v[216:217], v[178:179], v[188:189] op_sel:[0,1,0] op_sel_hi:[1,1,1]
	v_pk_fma_f32 v[190:191], v[218:219], v[178:179], v[190:191] op_sel:[0,1,0] op_sel_hi:[1,1,1]
	ds_read_b128 v[216:219], v2 offset:59024
	s_waitcnt lgkmcnt(13)
	v_pk_fma_f32 v[192:193], v[220:221], v[178:179], v[192:193] op_sel:[0,1,0] op_sel_hi:[1,1,1]
	v_pk_fma_f32 v[194:195], v[222:223], v[178:179], v[194:195] op_sel:[0,1,0] op_sel_hi:[1,1,1]
	ds_read_b128 v[220:223], v2 offset:59040
	s_waitcnt lgkmcnt(12)
	v_pk_fma_f32 v[196:197], v[224:225], v[178:179], v[196:197] op_sel:[0,1,0] op_sel_hi:[1,1,1]
	v_pk_fma_f32 v[198:199], v[226:227], v[178:179], v[198:199] op_sel:[0,1,0] op_sel_hi:[1,1,1]
	ds_read_b128 v[224:227], v2 offset:59056
	s_waitcnt lgkmcnt(12)
	v_pk_fma_f32 v[200:201], v[228:229], v[178:179], v[200:201] op_sel:[0,1,0] op_sel_hi:[1,1,1]
	v_pk_fma_f32 v[202:203], v[230:231], v[178:179], v[202:203] op_sel:[0,1,0] op_sel_hi:[1,1,1]
	ds_read_b128 v[228:231], v2 offset:59072
	s_waitcnt lgkmcnt(12)
	v_pk_fma_f32 v[204:205], v[240:241], v[178:179], v[204:205] op_sel:[0,1,0] op_sel_hi:[1,1,1]
	v_pk_fma_f32 v[206:207], v[242:243], v[178:179], v[206:207] op_sel:[0,1,0] op_sel_hi:[1,1,1]
	ds_read_b128 v[240:243], v2 offset:59088
	s_waitcnt lgkmcnt(12)
	v_pk_fma_f32 v[180:181], v[244:245], v[180:181], v[180:181] op_sel:[0,0,0] op_sel_hi:[1,0,1]
	v_pk_fma_f32 v[182:183], v[246:247], v[180:181], v[182:183] op_sel:[0,0,0] op_sel_hi:[1,0,1]
	v_cvt_pk_bf16_f32 v3, v180, v2
	ds_write_b16 v113, v3 offset:32832
	ds_read_b128 v[244:247], v2 offset:59104
	s_waitcnt lgkmcnt(13)
	v_pk_fma_f32 v[184:185], v[38:39], v[180:181], v[184:185] op_sel:[0,0,0] op_sel_hi:[1,0,1]
	v_pk_fma_f32 v[186:187], v[40:41], v[180:181], v[186:187] op_sel:[0,0,0] op_sel_hi:[1,0,1]
	ds_read_b128 v[38:41], v2 offset:59120
	s_waitcnt lgkmcnt(13)
	v_pk_fma_f32 v[188:189], v[42:43], v[180:181], v[188:189] op_sel:[0,0,0] op_sel_hi:[1,0,1]
	v_pk_fma_f32 v[190:191], v[44:45], v[180:181], v[190:191] op_sel:[0,0,0] op_sel_hi:[1,0,1]
	ds_read_b128 v[42:45], v2 offset:59152
	s_waitcnt lgkmcnt(13)
	v_pk_fma_f32 v[192:193], v[46:47], v[180:181], v[192:193] op_sel:[0,0,0] op_sel_hi:[1,0,1]
	v_pk_fma_f32 v[194:195], v[48:49], v[180:181], v[194:195] op_sel:[0,0,0] op_sel_hi:[1,0,1]
	ds_read_b128 v[46:49], v2 offset:59168
	s_waitcnt lgkmcnt(13)
	v_pk_fma_f32 v[196:197], v[50:51], v[180:181], v[196:197] op_sel:[0,0,0] op_sel_hi:[1,0,1]
	v_pk_fma_f32 v[198:199], v[52:53], v[180:181], v[198:199] op_sel:[0,0,0] op_sel_hi:[1,0,1]
	ds_read_b128 v[50:53], v2 offset:59184
	s_waitcnt lgkmcnt(12)
	v_pk_fma_f32 v[200:201], v[208:209], v[180:181], v[200:201] op_sel:[0,0,0] op_sel_hi:[1,0,1]
	v_pk_fma_f32 v[202:203], v[210:211], v[180:181], v[202:203] op_sel:[0,0,0] op_sel_hi:[1,0,1]
	ds_read_b128 v[208:211], v2 offset:59200
	s_waitcnt lgkmcnt(12)
	v_pk_fma_f32 v[204:205], v[212:213], v[180:181], v[204:205] op_sel:[0,0,0] op_sel_hi:[1,0,1]
	v_pk_fma_f32 v[206:207], v[214:215], v[180:181], v[206:207] op_sel:[0,0,0] op_sel_hi:[1,0,1]
	ds_read_b128 v[212:215], v2 offset:59216
	s_waitcnt lgkmcnt(12)
	v_pk_fma_f32 v[182:183], v[218:219], v[180:181], v[182:183] op_sel:[0,1,0] op_sel_hi:[1,1,1]
	v_cvt_pk_bf16_f32 v232, v181, v2
	ds_write_b16 v113, v232 offset:32976
	ds_read_b128 v[216:219], v2 offset:59232
	s_waitcnt lgkmcnt(13)
	v_pk_fma_f32 v[184:185], v[220:221], v[180:181], v[184:185] op_sel:[0,1,0] op_sel_hi:[1,1,1]
	v_pk_fma_f32 v[186:187], v[222:223], v[180:181], v[186:187] op_sel:[0,1,0] op_sel_hi:[1,1,1]
	ds_read_b128 v[220:223], v2 offset:59248
	s_waitcnt lgkmcnt(13)
	v_pk_fma_f32 v[188:189], v[224:225], v[180:181], v[188:189] op_sel:[0,1,0] op_sel_hi:[1,1,1]
	v_pk_fma_f32 v[190:191], v[226:227], v[180:181], v[190:191] op_sel:[0,1,0] op_sel_hi:[1,1,1]
	ds_read_b128 v[224:227], v2 offset:59296
	s_waitcnt lgkmcnt(13)
	v_pk_fma_f32 v[192:193], v[228:229], v[180:181], v[192:193] op_sel:[0,1,0] op_sel_hi:[1,1,1]
	v_pk_fma_f32 v[194:195], v[230:231], v[180:181], v[194:195] op_sel:[0,1,0] op_sel_hi:[1,1,1]
	ds_read_b128 v[228:231], v2 offset:59312
	s_waitcnt lgkmcnt(13)
	v_pk_fma_f32 v[196:197], v[240:241], v[180:181], v[196:197] op_sel:[0,1,0] op_sel_hi:[1,1,1]
	v_pk_fma_f32 v[198:199], v[242:243], v[180:181], v[198:199] op_sel:[0,1,0] op_sel_hi:[1,1,1]
	ds_read_b128 v[240:243], v2 offset:59328
	s_waitcnt lgkmcnt(12)
	v_pk_fma_f32 v[200:201], v[244:245], v[180:181], v[200:201] op_sel:[0,1,0] op_sel_hi:[1,1,1]
	v_pk_fma_f32 v[202:203], v[246:247], v[180:181], v[202:203] op_sel:[0,1,0] op_sel_hi:[1,1,1]
	ds_read_b128 v[244:247], v2 offset:59344
	s_waitcnt lgkmcnt(12)
	v_pk_fma_f32 v[204:205], v[38:39], v[180:181], v[204:205] op_sel:[0,1,0] op_sel_hi:[1,1,1]
	v_pk_fma_f32 v[206:207], v[40:41], v[180:181], v[206:207] op_sel:[0,1,0] op_sel_hi:[1,1,1]
	ds_read_b128 v[38:41], v2 offset:59360
	s_waitcnt lgkmcnt(12)
	v_pk_fma_f32 v[182:183], v[44:45], v[182:183], v[182:183] op_sel:[0,0,0] op_sel_hi:[1,0,1]
	v_cvt_pk_bf16_f32 v233, v182, v2
	ds_write_b16 v113, v233 offset:33120
	ds_read_b128 v[42:45], v2 offset:59376
	s_waitcnt lgkmcnt(13)
	v_pk_fma_f32 v[184:185], v[46:47], v[182:183], v[184:185] op_sel:[0,0,0] op_sel_hi:[1,0,1]
	v_pk_fma_f32 v[186:187], v[48:49], v[182:183], v[186:187] op_sel:[0,0,0] op_sel_hi:[1,0,1]
	ds_read_b128 v[46:49], v2 offset:59424
	s_waitcnt lgkmcnt(13)
	v_pk_fma_f32 v[188:189], v[50:51], v[182:183], v[188:189] op_sel:[0,0,0] op_sel_hi:[1,0,1]
	v_pk_fma_f32 v[190:191], v[52:53], v[182:183], v[190:191] op_sel:[0,0,0] op_sel_hi:[1,0,1]
	ds_read_b128 v[50:53], v2 offset:59440
	s_waitcnt lgkmcnt(13)
	v_pk_fma_f32 v[192:193], v[208:209], v[182:183], v[192:193] op_sel:[0,0,0] op_sel_hi:[1,0,1]
	v_pk_fma_f32 v[194:195], v[210:211], v[182:183], v[194:195] op_sel:[0,0,0] op_sel_hi:[1,0,1]
	ds_read_b128 v[208:211], v2 offset:59456
	s_waitcnt lgkmcnt(13)
	v_pk_fma_f32 v[196:197], v[212:213], v[182:183], v[196:197] op_sel:[0,0,0] op_sel_hi:[1,0,1]
	v_pk_fma_f32 v[198:199], v[214:215], v[182:183], v[198:199] op_sel:[0,0,0] op_sel_hi:[1,0,1]
	ds_read_b128 v[212:215], v2 offset:59472
	s_waitcnt lgkmcnt(12)
	v_pk_fma_f32 v[200:201], v[216:217], v[182:183], v[200:201] op_sel:[0,0,0] op_sel_hi:[1,0,1]
	v_pk_fma_f32 v[202:203], v[218:219], v[182:183], v[202:203] op_sel:[0,0,0] op_sel_hi:[1,0,1]
	ds_read_b128 v[216:219], v2 offset:59488
	s_waitcnt lgkmcnt(12)
	v_pk_fma_f32 v[204:205], v[220:221], v[182:183], v[204:205] op_sel:[0,0,0] op_sel_hi:[1,0,1]
	v_pk_fma_f32 v[206:207], v[222:223], v[182:183], v[206:207] op_sel:[0,0,0] op_sel_hi:[1,0,1]
	ds_read_b128 v[220:223], v2 offset:59504
	s_waitcnt lgkmcnt(12)
	v_pk_fma_f32 v[184:185], v[224:225], v[182:183], v[184:185] op_sel:[0,1,0] op_sel_hi:[1,1,1]
	v_pk_fma_f32 v[186:187], v[226:227], v[182:183], v[186:187] op_sel:[0,1,0] op_sel_hi:[1,1,1]
	v_cvt_pk_bf16_f32 v248, v183, v2
	ds_write_b16 v113, v248 offset:33264
	ds_read_b128 v[224:227], v2 offset:59552
	s_waitcnt lgkmcnt(13)
	v_pk_fma_f32 v[188:189], v[228:229], v[182:183], v[188:189] op_sel:[0,1,0] op_sel_hi:[1,1,1]
	v_pk_fma_f32 v[190:191], v[230:231], v[182:183], v[190:191] op_sel:[0,1,0] op_sel_hi:[1,1,1]
	ds_read_b128 v[228:231], v2 offset:59568
	s_waitcnt lgkmcnt(13)
	v_pk_fma_f32 v[192:193], v[240:241], v[182:183], v[192:193] op_sel:[0,1,0] op_sel_hi:[1,1,1]
	v_pk_fma_f32 v[194:195], v[242:243], v[182:183], v[194:195] op_sel:[0,1,0] op_sel_hi:[1,1,1]
	ds_read_b128 v[240:243], v2 offset:59584
	s_waitcnt lgkmcnt(13)
	v_pk_fma_f32 v[196:197], v[244:245], v[182:183], v[196:197] op_sel:[0,1,0] op_sel_hi:[1,1,1]
	v_pk_fma_f32 v[198:199], v[246:247], v[182:183], v[198:199] op_sel:[0,1,0] op_sel_hi:[1,1,1]
	ds_read_b128 v[244:247], v2 offset:59600
	s_waitcnt lgkmcnt(13)
	v_pk_fma_f32 v[200:201], v[38:39], v[182:183], v[200:201] op_sel:[0,1,0] op_sel_hi:[1,1,1]
	v_pk_fma_f32 v[202:203], v[40:41], v[182:183], v[202:203] op_sel:[0,1,0] op_sel_hi:[1,1,1]
	ds_read_b128 v[38:41], v2 offset:59616
	s_waitcnt lgkmcnt(12)
	v_pk_fma_f32 v[204:205], v[42:43], v[182:183], v[204:205] op_sel:[0,1,0] op_sel_hi:[1,1,1]
	v_pk_fma_f32 v[206:207], v[44:45], v[182:183], v[206:207] op_sel:[0,1,0] op_sel_hi:[1,1,1]
	ds_read_b128 v[42:45], v2 offset:59632
	s_waitcnt lgkmcnt(12)
	v_pk_fma_f32 v[184:185], v[46:47], v[184:185], v[184:185] op_sel:[0,0,0] op_sel_hi:[1,0,1]
	v_pk_fma_f32 v[186:187], v[48:49], v[184:185], v[186:187] op_sel:[0,0,0] op_sel_hi:[1,0,1]
	v_cvt_pk_bf16_f32 v3, v184, v2
	ds_write_b16 v113, v3 offset:33408
	ds_read_b128 v[46:49], v2 offset:59680
	s_waitcnt lgkmcnt(13)
	v_pk_fma_f32 v[188:189], v[50:51], v[184:185], v[188:189] op_sel:[0,0,0] op_sel_hi:[1,0,1]
	v_pk_fma_f32 v[190:191], v[52:53], v[184:185], v[190:191] op_sel:[0,0,0] op_sel_hi:[1,0,1]
	ds_read_b128 v[50:53], v2 offset:59696
	s_waitcnt lgkmcnt(13)
	v_pk_fma_f32 v[192:193], v[208:209], v[184:185], v[192:193] op_sel:[0,0,0] op_sel_hi:[1,0,1]
	v_pk_fma_f32 v[194:195], v[210:211], v[184:185], v[194:195] op_sel:[0,0,0] op_sel_hi:[1,0,1]
	ds_read_b128 v[208:211], v2 offset:59712
	s_waitcnt lgkmcnt(13)
	v_pk_fma_f32 v[196:197], v[212:213], v[184:185], v[196:197] op_sel:[0,0,0] op_sel_hi:[1,0,1]
	v_pk_fma_f32 v[198:199], v[214:215], v[184:185], v[198:199] op_sel:[0,0,0] op_sel_hi:[1,0,1]
	ds_read_b128 v[212:215], v2 offset:59728
	s_waitcnt lgkmcnt(13)
	v_pk_fma_f32 v[200:201], v[216:217], v[184:185], v[200:201] op_sel:[0,0,0] op_sel_hi:[1,0,1]
	v_pk_fma_f32 v[202:203], v[218:219], v[184:185], v[202:203] op_sel:[0,0,0] op_sel_hi:[1,0,1]
	ds_read_b128 v[216:219], v2 offset:59744
	s_waitcnt lgkmcnt(13)
	v_pk_fma_f32 v[204:205], v[220:221], v[184:185], v[204:205] op_sel:[0,0,0] op_sel_hi:[1,0,1]
	v_pk_fma_f32 v[206:207], v[222:223], v[184:185], v[206:207] op_sel:[0,0,0] op_sel_hi:[1,0,1]
	ds_read_b128 v[220:223], v2 offset:59760
	s_waitcnt lgkmcnt(12)
	v_pk_fma_f32 v[186:187], v[226:227], v[184:185], v[186:187] op_sel:[0,1,0] op_sel_hi:[1,1,1]
	v_cvt_pk_bf16_f32 v232, v185, v2
	ds_write_b16 v113, v232 offset:33552
	ds_read_b128 v[224:227], v2 offset:59824
	s_waitcnt lgkmcnt(13)
	v_pk_fma_f32 v[188:189], v[228:229], v[184:185], v[188:189] op_sel:[0,1,0] op_sel_hi:[1,1,1]
	v_pk_fma_f32 v[190:191], v[230:231], v[184:185], v[190:191] op_sel:[0,1,0] op_sel_hi:[1,1,1]
	ds_read_b128 v[228:231], v2 offset:59840
	s_waitcnt lgkmcnt(13)
	v_pk_fma_f32 v[192:193], v[240:241], v[184:185], v[192:193] op_sel:[0,1,0] op_sel_hi:[1,1,1]
	v_pk_fma_f32 v[194:195], v[242:243], v[184:185], v[194:195] op_sel:[0,1,0] op_sel_hi:[1,1,1]
	ds_read_b128 v[240:243], v2 offset:59856
	s_waitcnt lgkmcnt(13)
	v_pk_fma_f32 v[196:197], v[244:245], v[184:185], v[196:197] op_sel:[0,1,0] op_sel_hi:[1,1,1]
	v_pk_fma_f32 v[198:199], v[246:247], v[184:185], v[198:199] op_sel:[0,1,0] op_sel_hi:[1,1,1]
	ds_read_b128 v[244:247], v2 offset:59872
	s_waitcnt lgkmcnt(13)
	v_pk_fma_f32 v[200:201], v[38:39], v[184:185], v[200:201] op_sel:[0,1,0] op_sel_hi:[1,1,1]
	v_pk_fma_f32 v[202:203], v[40:41], v[184:185], v[202:203] op_sel:[0,1,0] op_sel_hi:[1,1,1]
	ds_read_b128 v[38:41], v2 offset:59888
	s_waitcnt lgkmcnt(13)
	v_pk_fma_f32 v[204:205], v[42:43], v[184:185], v[204:205] op_sel:[0,1,0] op_sel_hi:[1,1,1]
	v_pk_fma_f32 v[206:207], v[44:45], v[184:185], v[206:207] op_sel:[0,1,0] op_sel_hi:[1,1,1]
	ds_read_b128 v[42:45], v2 offset:59952
	s_waitcnt lgkmcnt(12)
	v_pk_fma_f32 v[186:187], v[48:49], v[186:187], v[186:187] op_sel:[0,0,0] op_sel_hi:[1,0,1]
	v_cvt_pk_bf16_f32 v233, v186, v2
	ds_write_b16 v113, v233 offset:33696
	ds_read_b128 v[46:49], v2 offset:59968
	s_waitcnt lgkmcnt(13)
	v_pk_fma_f32 v[188:189], v[50:51], v[186:187], v[188:189] op_sel:[0,0,0] op_sel_hi:[1,0,1]
	v_pk_fma_f32 v[190:191], v[52:53], v[186:187], v[190:191] op_sel:[0,0,0] op_sel_hi:[1,0,1]
	ds_read_b128 v[50:53], v2 offset:59984
	s_waitcnt lgkmcnt(13)
	v_pk_fma_f32 v[192:193], v[208:209], v[186:187], v[192:193] op_sel:[0,0,0] op_sel_hi:[1,0,1]
	v_pk_fma_f32 v[194:195], v[210:211], v[186:187], v[194:195] op_sel:[0,0,0] op_sel_hi:[1,0,1]
	ds_read_b128 v[208:211], v2 offset:60000
	s_waitcnt lgkmcnt(13)
	v_pk_fma_f32 v[196:197], v[212:213], v[186:187], v[196:197] op_sel:[0,0,0] op_sel_hi:[1,0,1]
	v_pk_fma_f32 v[198:199], v[214:215], v[186:187], v[198:199] op_sel:[0,0,0] op_sel_hi:[1,0,1]
	ds_read_b128 v[212:215], v2 offset:60016
	s_waitcnt lgkmcnt(13)
	v_pk_fma_f32 v[200:201], v[216:217], v[186:187], v[200:201] op_sel:[0,0,0] op_sel_hi:[1,0,1]
	v_pk_fma_f32 v[202:203], v[218:219], v[186:187], v[202:203] op_sel:[0,0,0] op_sel_hi:[1,0,1]
	ds_read_b128 v[216:219], v2 offset:60080
	s_waitcnt lgkmcnt(13)
	v_pk_fma_f32 v[204:205], v[220:221], v[186:187], v[204:205] op_sel:[0,0,0] op_sel_hi:[1,0,1]
	v_pk_fma_f32 v[206:207], v[222:223], v[186:187], v[206:207] op_sel:[0,0,0] op_sel_hi:[1,0,1]
	ds_read_b128 v[220:223], v2 offset:60096
	s_waitcnt lgkmcnt(12)
	v_pk_fma_f32 v[188:189], v[224:225], v[186:187], v[188:189] op_sel:[0,1,0] op_sel_hi:[1,1,1]
	v_pk_fma_f32 v[190:191], v[226:227], v[186:187], v[190:191] op_sel:[0,1,0] op_sel_hi:[1,1,1]
	v_cvt_pk_bf16_f32 v248, v187, v2
	ds_write_b16 v113, v248 offset:33840
	ds_read_b128 v[224:227], v2 offset:60112
	s_waitcnt lgkmcnt(13)
	v_pk_fma_f32 v[192:193], v[228:229], v[186:187], v[192:193] op_sel:[0,1,0] op_sel_hi:[1,1,1]
	v_pk_fma_f32 v[194:195], v[230:231], v[186:187], v[194:195] op_sel:[0,1,0] op_sel_hi:[1,1,1]
	ds_read_b128 v[228:231], v2 offset:60128
	s_waitcnt lgkmcnt(13)
	v_pk_fma_f32 v[196:197], v[240:241], v[186:187], v[196:197] op_sel:[0,1,0] op_sel_hi:[1,1,1]
	v_pk_fma_f32 v[198:199], v[242:243], v[186:187], v[198:199] op_sel:[0,1,0] op_sel_hi:[1,1,1]
	ds_read_b128 v[240:243], v2 offset:60144
	s_waitcnt lgkmcnt(13)
	v_pk_fma_f32 v[200:201], v[244:245], v[186:187], v[200:201] op_sel:[0,1,0] op_sel_hi:[1,1,1]
	v_pk_fma_f32 v[202:203], v[246:247], v[186:187], v[202:203] op_sel:[0,1,0] op_sel_hi:[1,1,1]
	ds_read_b128 v[244:247], v2 offset:60208
	s_waitcnt lgkmcnt(13)
	v_pk_fma_f32 v[204:205], v[38:39], v[186:187], v[204:205] op_sel:[0,1,0] op_sel_hi:[1,1,1]
	v_pk_fma_f32 v[206:207], v[40:41], v[186:187], v[206:207] op_sel:[0,1,0] op_sel_hi:[1,1,1]
	ds_read_b128 v[38:41], v2 offset:60224
	s_waitcnt lgkmcnt(13)
	v_pk_fma_f32 v[188:189], v[42:43], v[188:189], v[188:189] op_sel:[0,0,0] op_sel_hi:[1,0,1]
	v_pk_fma_f32 v[190:191], v[44:45], v[188:189], v[190:191] op_sel:[0,0,0] op_sel_hi:[1,0,1]
	v_cvt_pk_bf16_f32 v3, v188, v2
	ds_write_b16 v113, v3 offset:33984
	ds_read_b128 v[42:45], v2 offset:60240
	s_waitcnt lgkmcnt(13)
	v_pk_fma_f32 v[192:193], v[46:47], v[188:189], v[192:193] op_sel:[0,0,0] op_sel_hi:[1,0,1]
	v_pk_fma_f32 v[194:195], v[48:49], v[188:189], v[194:195] op_sel:[0,0,0] op_sel_hi:[1,0,1]
	ds_read_b128 v[46:49], v2 offset:60256
	s_waitcnt lgkmcnt(13)
	v_pk_fma_f32 v[196:197], v[50:51], v[188:189], v[196:197] op_sel:[0,0,0] op_sel_hi:[1,0,1]
	v_pk_fma_f32 v[198:199], v[52:53], v[188:189], v[198:199] op_sel:[0,0,0] op_sel_hi:[1,0,1]
	ds_read_b128 v[50:53], v2 offset:60272
	s_waitcnt lgkmcnt(13)
	v_pk_fma_f32 v[200:201], v[208:209], v[188:189], v[200:201] op_sel:[0,0,0] op_sel_hi:[1,0,1]
	v_pk_fma_f32 v[202:203], v[210:211], v[188:189], v[202:203] op_sel:[0,0,0] op_sel_hi:[1,0,1]
	ds_read_b128 v[208:211], v2 offset:60352
	s_waitcnt lgkmcnt(13)
	v_pk_fma_f32 v[204:205], v[212:213], v[188:189], v[204:205] op_sel:[0,0,0] op_sel_hi:[1,0,1]
	v_pk_fma_f32 v[206:207], v[214:215], v[188:189], v[206:207] op_sel:[0,0,0] op_sel_hi:[1,0,1]
	ds_read_b128 v[212:215], v2 offset:60368
	s_waitcnt lgkmcnt(13)
	v_pk_fma_f32 v[190:191], v[218:219], v[188:189], v[190:191] op_sel:[0,1,0] op_sel_hi:[1,1,1]
	v_cvt_pk_bf16_f32 v232, v189, v2
	ds_write_b16 v113, v232 offset:34128
	ds_read_b128 v[216:219], v2 offset:60384
	s_waitcnt lgkmcnt(14)
	v_pk_fma_f32 v[192:193], v[220:221], v[188:189], v[192:193] op_sel:[0,1,0] op_sel_hi:[1,1,1]
	v_pk_fma_f32 v[194:195], v[222:223], v[188:189], v[194:195] op_sel:[0,1,0] op_sel_hi:[1,1,1]
	ds_read_b128 v[220:223], v2 offset:60400
	s_waitcnt lgkmcnt(13)
	v_pk_fma_f32 v[196:197], v[224:225], v[188:189], v[196:197] op_sel:[0,1,0] op_sel_hi:[1,1,1]
	v_pk_fma_f32 v[198:199], v[226:227], v[188:189], v[198:199] op_sel:[0,1,0] op_sel_hi:[1,1,1]
	ds_read_b128 v[224:227], v2 offset:60480
	s_waitcnt lgkmcnt(13)
	v_pk_fma_f32 v[200:201], v[228:229], v[188:189], v[200:201] op_sel:[0,1,0] op_sel_hi:[1,1,1]
	v_pk_fma_f32 v[202:203], v[230:231], v[188:189], v[202:203] op_sel:[0,1,0] op_sel_hi:[1,1,1]
	ds_read_b128 v[228:231], v2 offset:60496
	s_waitcnt lgkmcnt(13)
	v_pk_fma_f32 v[204:205], v[240:241], v[188:189], v[204:205] op_sel:[0,1,0] op_sel_hi:[1,1,1]
	v_pk_fma_f32 v[206:207], v[242:243], v[188:189], v[206:207] op_sel:[0,1,0] op_sel_hi:[1,1,1]
	ds_read_b128 v[240:243], v2 offset:60512
	s_waitcnt lgkmcnt(13)
	v_pk_fma_f32 v[190:191], v[246:247], v[190:191], v[190:191] op_sel:[0,0,0] op_sel_hi:[1,0,1]
	v_cvt_pk_bf16_f32 v233, v190, v2
	ds_write_b16 v113, v233 offset:34272
	ds_read_b128 v[244:247], v2 offset:60528
	s_waitcnt lgkmcnt(14)
	v_pk_fma_f32 v[192:193], v[38:39], v[190:191], v[192:193] op_sel:[0,0,0] op_sel_hi:[1,0,1]
	v_pk_fma_f32 v[194:195], v[40:41], v[190:191], v[194:195] op_sel:[0,0,0] op_sel_hi:[1,0,1]
	ds_read_b128 v[38:41], v2 offset:60608
	s_waitcnt lgkmcnt(13)
	v_pk_fma_f32 v[196:197], v[42:43], v[190:191], v[196:197] op_sel:[0,0,0] op_sel_hi:[1,0,1]
	v_pk_fma_f32 v[198:199], v[44:45], v[190:191], v[198:199] op_sel:[0,0,0] op_sel_hi:[1,0,1]
	ds_read_b128 v[42:45], v2 offset:60624
	s_waitcnt lgkmcnt(13)
	v_pk_fma_f32 v[200:201], v[46:47], v[190:191], v[200:201] op_sel:[0,0,0] op_sel_hi:[1,0,1]
	v_pk_fma_f32 v[202:203], v[48:49], v[190:191], v[202:203] op_sel:[0,0,0] op_sel_hi:[1,0,1]
	ds_read_b128 v[46:49], v2 offset:60640
	s_waitcnt lgkmcnt(13)
	v_pk_fma_f32 v[204:205], v[50:51], v[190:191], v[204:205] op_sel:[0,0,0] op_sel_hi:[1,0,1]
	v_pk_fma_f32 v[206:207], v[52:53], v[190:191], v[206:207] op_sel:[0,0,0] op_sel_hi:[1,0,1]
	ds_read_b128 v[50:53], v2 offset:60656
	s_waitcnt lgkmcnt(13)
	v_pk_fma_f32 v[192:193], v[208:209], v[190:191], v[192:193] op_sel:[0,1,0] op_sel_hi:[1,1,1]
	v_pk_fma_f32 v[194:195], v[210:211], v[190:191], v[194:195] op_sel:[0,1,0] op_sel_hi:[1,1,1]
	v_cvt_pk_bf16_f32 v248, v191, v2
	ds_write_b16 v113, v248 offset:34416
	ds_read_b128 v[208:211], v2 offset:60736
	s_waitcnt lgkmcnt(14)
	v_pk_fma_f32 v[196:197], v[212:213], v[190:191], v[196:197] op_sel:[0,1,0] op_sel_hi:[1,1,1]
	v_pk_fma_f32 v[198:199], v[214:215], v[190:191], v[198:199] op_sel:[0,1,0] op_sel_hi:[1,1,1]
	ds_read_b128 v[212:215], v2 offset:60752
	s_waitcnt lgkmcnt(13)
	v_pk_fma_f32 v[200:201], v[216:217], v[190:191], v[200:201] op_sel:[0,1,0] op_sel_hi:[1,1,1]
	v_pk_fma_f32 v[202:203], v[218:219], v[190:191], v[202:203] op_sel:[0,1,0] op_sel_hi:[1,1,1]
	ds_read_b128 v[216:219], v2 offset:60768
	s_waitcnt lgkmcnt(13)
	v_pk_fma_f32 v[204:205], v[220:221], v[190:191], v[204:205] op_sel:[0,1,0] op_sel_hi:[1,1,1]
	v_pk_fma_f32 v[206:207], v[222:223], v[190:191], v[206:207] op_sel:[0,1,0] op_sel_hi:[1,1,1]
	ds_read_b128 v[220:223], v2 offset:60784
	s_waitcnt lgkmcnt(13)
	v_pk_fma_f32 v[192:193], v[224:225], v[192:193], v[192:193] op_sel:[0,0,0] op_sel_hi:[1,0,1]
	v_pk_fma_f32 v[194:195], v[226:227], v[192:193], v[194:195] op_sel:[0,0,0] op_sel_hi:[1,0,1]
	v_cvt_pk_bf16_f32 v3, v192, v2
	ds_write_b16 v113, v3 offset:34560
	ds_read_b128 v[224:227], v2 offset:60880
	s_waitcnt lgkmcnt(14)
	v_pk_fma_f32 v[196:197], v[228:229], v[192:193], v[196:197] op_sel:[0,0,0] op_sel_hi:[1,0,1]
	v_pk_fma_f32 v[198:199], v[230:231], v[192:193], v[198:199] op_sel:[0,0,0] op_sel_hi:[1,0,1]
	ds_read_b128 v[228:231], v2 offset:60896
	s_waitcnt lgkmcnt(14)
	v_pk_fma_f32 v[200:201], v[240:241], v[192:193], v[200:201] op_sel:[0,0,0] op_sel_hi:[1,0,1]
	v_pk_fma_f32 v[202:203], v[242:243], v[192:193], v[202:203] op_sel:[0,0,0] op_sel_hi:[1,0,1]
	ds_read_b128 v[240:243], v2 offset:60912
	s_waitcnt lgkmcnt(13)
	v_pk_fma_f32 v[204:205], v[244:245], v[192:193], v[204:205] op_sel:[0,0,0] op_sel_hi:[1,0,1]
	v_pk_fma_f32 v[206:207], v[246:247], v[192:193], v[206:207] op_sel:[0,0,0] op_sel_hi:[1,0,1]
	ds_read_b128 v[244:247], v2 offset:61008
	s_waitcnt lgkmcnt(13)
	v_pk_fma_f32 v[194:195], v[40:41], v[192:193], v[194:195] op_sel:[0,1,0] op_sel_hi:[1,1,1]
	v_cvt_pk_bf16_f32 v232, v193, v2
	ds_write_b16 v113, v232 offset:34704
	ds_read_b128 v[38:41], v2 offset:61024
	s_waitcnt lgkmcnt(14)
	v_pk_fma_f32 v[196:197], v[42:43], v[192:193], v[196:197] op_sel:[0,1,0] op_sel_hi:[1,1,1]
	v_pk_fma_f32 v[198:199], v[44:45], v[192:193], v[198:199] op_sel:[0,1,0] op_sel_hi:[1,1,1]
	ds_read_b128 v[42:45], v2 offset:61040
	s_waitcnt lgkmcnt(14)
	v_pk_fma_f32 v[200:201], v[46:47], v[192:193], v[200:201] op_sel:[0,1,0] op_sel_hi:[1,1,1]
	v_pk_fma_f32 v[202:203], v[48:49], v[192:193], v[202:203] op_sel:[0,1,0] op_sel_hi:[1,1,1]
	ds_read_b128 v[46:49], v2 offset:61136
	s_waitcnt lgkmcnt(14)
	v_pk_fma_f32 v[204:205], v[50:51], v[192:193], v[204:205] op_sel:[0,1,0] op_sel_hi:[1,1,1]
	v_pk_fma_f32 v[206:207], v[52:53], v[192:193], v[206:207] op_sel:[0,1,0] op_sel_hi:[1,1,1]
	ds_read_b128 v[50:53], v2 offset:61152
	s_waitcnt lgkmcnt(13)
	v_pk_fma_f32 v[194:195], v[210:211], v[194:195], v[194:195] op_sel:[0,0,0] op_sel_hi:[1,0,1]
	v_cvt_pk_bf16_f32 v233, v194, v2
	ds_write_b16 v113, v233 offset:34848
	ds_read_b128 v[208:211], v2 offset:61168
	s_waitcnt lgkmcnt(14)
	v_pk_fma_f32 v[196:197], v[212:213], v[194:195], v[196:197] op_sel:[0,0,0] op_sel_hi:[1,0,1]
	v_pk_fma_f32 v[198:199], v[214:215], v[194:195], v[198:199] op_sel:[0,0,0] op_sel_hi:[1,0,1]
	ds_read_b128 v[212:215], v2 offset:61264
	s_waitcnt lgkmcnt(14)
	v_pk_fma_f32 v[200:201], v[216:217], v[194:195], v[200:201] op_sel:[0,0,0] op_sel_hi:[1,0,1]
	v_pk_fma_f32 v[202:203], v[218:219], v[194:195], v[202:203] op_sel:[0,0,0] op_sel_hi:[1,0,1]
	ds_read_b128 v[216:219], v2 offset:61280
	s_waitcnt lgkmcnt(14)
	v_pk_fma_f32 v[204:205], v[220:221], v[194:195], v[204:205] op_sel:[0,0,0] op_sel_hi:[1,0,1]
	v_pk_fma_f32 v[206:207], v[222:223], v[194:195], v[206:207] op_sel:[0,0,0] op_sel_hi:[1,0,1]
	ds_read_b128 v[220:223], v2 offset:61296
	s_waitcnt lgkmcnt(13)
	v_pk_fma_f32 v[196:197], v[224:225], v[194:195], v[196:197] op_sel:[0,1,0] op_sel_hi:[1,1,1]
	v_pk_fma_f32 v[198:199], v[226:227], v[194:195], v[198:199] op_sel:[0,1,0] op_sel_hi:[1,1,1]
	v_cvt_pk_bf16_f32 v248, v195, v2
	ds_write_b16 v113, v248 offset:34992
	ds_read_b128 v[224:227], v2 offset:61408
	s_waitcnt lgkmcnt(14)
	v_pk_fma_f32 v[200:201], v[228:229], v[194:195], v[200:201] op_sel:[0,1,0] op_sel_hi:[1,1,1]
	v_pk_fma_f32 v[202:203], v[230:231], v[194:195], v[202:203] op_sel:[0,1,0] op_sel_hi:[1,1,1]
	ds_read_b128 v[228:231], v2 offset:61424
	s_waitcnt lgkmcnt(14)
	v_pk_fma_f32 v[204:205], v[240:241], v[194:195], v[204:205] op_sel:[0,1,0] op_sel_hi:[1,1,1]
	v_pk_fma_f32 v[206:207], v[242:243], v[194:195], v[206:207] op_sel:[0,1,0] op_sel_hi:[1,1,1]
	ds_read_b128 v[240:243], v2 offset:61536
	s_waitcnt lgkmcnt(14)
	v_pk_fma_f32 v[196:197], v[244:245], v[196:197], v[196:197] op_sel:[0,0,0] op_sel_hi:[1,0,1]
	v_pk_fma_f32 v[198:199], v[246:247], v[196:197], v[198:199] op_sel:[0,0,0] op_sel_hi:[1,0,1]
	v_cvt_pk_bf16_f32 v3, v196, v2
	ds_write_b16 v113, v3 offset:35136
	s_waitcnt lgkmcnt(14)
	ds_read_b128 v[244:247], v2 offset:61552
	s_waitcnt lgkmcnt(14)
	v_pk_fma_f32 v[200:201], v[38:39], v[196:197], v[200:201] op_sel:[0,0,0] op_sel_hi:[1,0,1]
	v_pk_fma_f32 v[202:203], v[40:41], v[196:197], v[202:203] op_sel:[0,0,0] op_sel_hi:[1,0,1]
	ds_read_b128 v[38:41], v2 offset:61664
	s_waitcnt lgkmcnt(14)
	v_pk_fma_f32 v[204:205], v[42:43], v[196:197], v[204:205] op_sel:[0,0,0] op_sel_hi:[1,0,1]
	v_pk_fma_f32 v[206:207], v[44:45], v[196:197], v[206:207] op_sel:[0,0,0] op_sel_hi:[1,0,1]
	ds_read_b128 v[42:45], v2 offset:61680
	s_waitcnt lgkmcnt(14)
	v_pk_fma_f32 v[198:199], v[48:49], v[196:197], v[198:199] op_sel:[0,1,0] op_sel_hi:[1,1,1]
	v_cvt_pk_bf16_f32 v232, v197, v2
	ds_write_b16 v113, v232 offset:35280
	s_waitcnt lgkmcnt(14)
	ds_read_b128 v[46:49], v2 offset:61792
	v_pk_fma_f32 v[200:201], v[50:51], v[196:197], v[200:201] op_sel:[0,1,0] op_sel_hi:[1,1,1]
	v_pk_fma_f32 v[202:203], v[52:53], v[196:197], v[202:203] op_sel:[0,1,0] op_sel_hi:[1,1,1]
	s_waitcnt lgkmcnt(14)
	ds_read_b128 v[50:53], v2 offset:61808
	s_waitcnt lgkmcnt(14)
	v_pk_fma_f32 v[204:205], v[208:209], v[196:197], v[204:205] op_sel:[0,1,0] op_sel_hi:[1,1,1]
	v_pk_fma_f32 v[206:207], v[210:211], v[196:197], v[206:207] op_sel:[0,1,0] op_sel_hi:[1,1,1]
	ds_read_b128 v[208:211], v2 offset:61936
	s_waitcnt lgkmcnt(14)
	v_pk_fma_f32 v[198:199], v[214:215], v[198:199], v[198:199] op_sel:[0,0,0] op_sel_hi:[1,0,1]
	v_cvt_pk_bf16_f32 v233, v198, v2
	ds_write_b16 v113, v233 offset:35424
	s_waitcnt lgkmcnt(14)
	ds_read_b128 v[212:215], v2 offset:62064
	v_pk_fma_f32 v[200:201], v[216:217], v[198:199], v[200:201] op_sel:[0,0,0] op_sel_hi:[1,0,1]
	v_pk_fma_f32 v[202:203], v[218:219], v[198:199], v[202:203] op_sel:[0,0,0] op_sel_hi:[1,0,1]
	s_waitcnt lgkmcnt(14)
	ds_read_b128 v[216:219], v2 offset:62192
	v_pk_fma_f32 v[204:205], v[220:221], v[198:199], v[204:205] op_sel:[0,0,0] op_sel_hi:[1,0,1]
	v_pk_fma_f32 v[206:207], v[222:223], v[198:199], v[206:207] op_sel:[0,0,0] op_sel_hi:[1,0,1]
	s_waitcnt lgkmcnt(14)
	ds_read_b128 v[220:223], v2 offset:62320
	s_waitcnt lgkmcnt(14)
	v_pk_fma_f32 v[200:201], v[224:225], v[198:199], v[200:201] op_sel:[0,1,0] op_sel_hi:[1,1,1]
	v_pk_fma_f32 v[202:203], v[226:227], v[198:199], v[202:203] op_sel:[0,1,0] op_sel_hi:[1,1,1]
	v_cvt_pk_bf16_f32 v248, v199, v2
	ds_write_b16 v113, v248 offset:35568
	s_waitcnt lgkmcnt(14)
	v_pk_fma_f32 v[204:205], v[228:229], v[198:199], v[204:205] op_sel:[0,1,0] op_sel_hi:[1,1,1]
	v_pk_fma_f32 v[206:207], v[230:231], v[198:199], v[206:207] op_sel:[0,1,0] op_sel_hi:[1,1,1]
	s_waitcnt lgkmcnt(13)
	v_pk_fma_f32 v[200:201], v[240:241], v[200:201], v[200:201] op_sel:[0,0,0] op_sel_hi:[1,0,1]
	v_pk_fma_f32 v[202:203], v[242:243], v[200:201], v[202:203] op_sel:[0,0,0] op_sel_hi:[1,0,1]
	v_cvt_pk_bf16_f32 v3, v200, v2
	ds_write_b16 v113, v3 offset:35712
	s_waitcnt lgkmcnt(12)
	v_pk_fma_f32 v[204:205], v[244:245], v[200:201], v[204:205] op_sel:[0,0,0] op_sel_hi:[1,0,1]
	v_pk_fma_f32 v[206:207], v[246:247], v[200:201], v[206:207] op_sel:[0,0,0] op_sel_hi:[1,0,1]
	s_waitcnt lgkmcnt(11)
	v_pk_fma_f32 v[202:203], v[40:41], v[200:201], v[202:203] op_sel:[0,1,0] op_sel_hi:[1,1,1]
	v_cvt_pk_bf16_f32 v232, v201, v2
	ds_write_b16 v113, v232 offset:35856
	s_waitcnt lgkmcnt(11)
	v_pk_fma_f32 v[204:205], v[42:43], v[200:201], v[204:205] op_sel:[0,1,0] op_sel_hi:[1,1,1]
	v_pk_fma_f32 v[206:207], v[44:45], v[200:201], v[206:207] op_sel:[0,1,0] op_sel_hi:[1,1,1]
	s_waitcnt lgkmcnt(9)
	v_pk_fma_f32 v[202:203], v[48:49], v[202:203], v[202:203] op_sel:[0,0,0] op_sel_hi:[1,0,1]
	v_cvt_pk_bf16_f32 v233, v202, v2
	ds_write_b16 v113, v233 offset:36000
	s_waitcnt lgkmcnt(9)
	v_pk_fma_f32 v[204:205], v[50:51], v[202:203], v[204:205] op_sel:[0,0,0] op_sel_hi:[1,0,1]
	v_pk_fma_f32 v[206:207], v[52:53], v[202:203], v[206:207] op_sel:[0,0,0] op_sel_hi:[1,0,1]
	s_waitcnt lgkmcnt(8)
	v_pk_fma_f32 v[204:205], v[208:209], v[202:203], v[204:205] op_sel:[0,1,0] op_sel_hi:[1,1,1]
	v_pk_fma_f32 v[206:207], v[210:211], v[202:203], v[206:207] op_sel:[0,1,0] op_sel_hi:[1,1,1]
	v_cvt_pk_bf16_f32 v248, v203, v2
	ds_write_b16 v113, v248 offset:36144
	s_waitcnt lgkmcnt(7)
	v_pk_fma_f32 v[204:205], v[212:213], v[204:205], v[204:205] op_sel:[0,0,0] op_sel_hi:[1,0,1]
	v_pk_fma_f32 v[206:207], v[214:215], v[204:205], v[206:207] op_sel:[0,0,0] op_sel_hi:[1,0,1]
	v_cvt_pk_bf16_f32 v3, v204, v2
	ds_write_b16 v113, v3 offset:36288
	s_waitcnt lgkmcnt(7)
	v_pk_fma_f32 v[206:207], v[218:219], v[204:205], v[206:207] op_sel:[0,1,0] op_sel_hi:[1,1,1]
	v_cvt_pk_bf16_f32 v232, v205, v2
	ds_write_b16 v113, v232 offset:36432
	s_waitcnt lgkmcnt(7)
	v_pk_fma_f32 v[206:207], v[222:223], v[206:207], v[206:207] op_sel:[0,0,0] op_sel_hi:[1,0,1]
	v_cvt_pk_bf16_f32 v233, v206, v2
	ds_write_b16 v113, v233 offset:36576
	v_cvt_pk_bf16_f32 v248, v207, v2
	ds_write_b16 v113, v248 offset:36720
